# v42 + merge(helper)/P4: per-unit acquire invalidate replaced by sc1 (agent-coherent) LDS-DMA operand loads
# baseline (speedup 1.0000x reference)
.Lpk_go:
	s_waitcnt vmcnt(0)
	s_lshl_b32 s12, s12, 6
	s_add_i32 s12, s12, s13
	v_mov_b32_e32 v2, s12
	v_mov_b32_e32 v0, s48
	ds_write_b32 v0, v2
	v_mov_b32_e32 v2, 1
	ds_write_b32 v0, v2 offset:8
	s_branch .LBB0_1228

.LBB0_1226:
	s_or_b64 exec, exec, s[14:15]
	s_waitcnt vmcnt(0)

.LBB0_1228:
	s_or_b64 exec, exec, s[10:11]
	s_waitcnt lgkmcnt(0)
	s_barrier
	ds_read_b32 v0, v140
	s_mov_b64 s[10:11], -1
	s_waitcnt lgkmcnt(0)
	v_readfirstlane_b32 s14, v0
	ds_read_b32 v1, v140 offset:8
	s_waitcnt lgkmcnt(0)
	v_readfirstlane_b32 s12, v1
	s_nop 1
	s_cmp_eq_u32 s12, 1
	s_cbranch_scc1 .Lp4_oneshot
	s_cmpk_gt_u32 s14, 0x1ff
	s_cbranch_scc1 .LBB0_1200
	v_mbcnt_lo_u32_b32 v2, -1, 0
	v_mbcnt_hi_u32_b32 v2, -1, v2
	s_lshl_b32 s4, s14, 2
	v_lshl_or_b32 v4, v2, 4, s66
	v_ashrrev_i32_e32 v0, 31, v4
	v_lshrrev_b32_e32 v0, 22, v0
	v_add_u32_e32 v0, v4, v0
	v_ashrrev_i32_e32 v0, 10, v0
	v_mul_i32_i24_e32 v1, 0x400, v0
	v_sub_u32_e32 v1, v4, v1
	v_lshrrev_b32_e32 v3, 4, v1
	v_bitop3_b32 v3, v3, v1, 32 bitop3:0x6c
	v_lshlrev_b32_e32 v1, 3, v0
	v_and_b32_e32 v5, -16, v1
	v_ashrrev_i32_e32 v1, 31, v3
	v_lshrrev_b32_e32 v1, 26, v1
	v_add_u32_e32 v6, v3, v1
	v_ashrrev_i32_e32 v1, 6, v6
	v_and_b32_e32 v6, 0xc0, v6
	v_sub_u32_e32 v3, v3, v6
	v_lshlrev_b32_e32 v7, 5, v0
	v_ashrrev_i16_sdwa v3, v141, sext(v3) dst_sel:DWORD dst_unused:UNUSED_PAD src0_sel:DWORD src1_sel:BYTE_0
	v_and_b32_e32 v7, 32, v7
	v_bfe_i32 v3, v3, 0, 16
	v_add_u32_e32 v5, v1, v5
	v_and_b32_e32 v9, 3, v1
	v_add_lshl_u32 v7, v7, v3, 1
	v_lshlrev_b32_e32 v6, 1, v5
	v_lshrrev_b32_e32 v8, 2, v5
	v_and_or_b32 v9, v5, s49, v9
	v_lshl_add_u32 v130, v5, 11, v7
	v_add_u32_e32 v5, 0x2000, v4
	v_ashrrev_i32_e32 v4, 31, v5
	v_lshrrev_b32_e32 v4, 22, v4
	v_and_b32_e32 v6, 24, v6
	v_and_b32_e32 v8, 4, v8
	v_add_u32_e32 v4, v5, v4
	v_or3_b32 v6, v9, v8, v6
	v_ashrrev_i32_e32 v4, 10, v4
	v_lshl_add_u32 v128, v6, 11, v7
	v_mul_i32_i24_e32 v6, 0x400, v4
	v_sub_u32_e32 v5, v5, v6
	v_lshrrev_b32_e32 v6, 4, v5
	v_bitop3_b32 v6, v6, v5, 32 bitop3:0x6c
	v_lshlrev_b32_e32 v5, 3, v4
	v_and_b32_e32 v7, -16, v5
	v_ashrrev_i32_e32 v5, 31, v6
	v_lshrrev_b32_e32 v5, 26, v5
	s_and_b32 s4, s4, 0x70
	s_lshr_b32 s15, s14, 5
	v_add_u32_e32 v8, v6, v5
	s_or_b32 s4, s4, s15
	v_ashrrev_i32_e32 v5, 6, v8
	v_and_b32_e32 v8, 0xffc0, v8
	s_and_b32 s20, s14, 3
	v_sub_u32_e32 v6, v6, v8
	s_lshl_b32 s21, s4, 19
	v_lshrrev_b16_e32 v8, 7, v6
	s_add_u32 s10, s64, s21
	v_and_b32_e32 v8, 1, v8
	s_addc_u32 s11, s65, 0
	s_lshl_b32 s16, s20, 19
	v_add_u32_e32 v7, v5, v7
	v_add_u16_e32 v6, v6, v8
	s_add_u32 s12, s50, s16
	v_lshlrev_b32_e32 v9, 5, v4
	v_ashrrev_i16_sdwa v6, v141, sext(v6) dst_sel:DWORD dst_unused:UNUSED_PAD src0_sel:DWORD src1_sel:BYTE_0
	v_lshlrev_b32_e32 v8, 1, v7
	v_lshrrev_b32_e32 v10, 2, v7
	v_and_b32_e32 v11, 3, v5
	s_addc_u32 s13, s51, 0
	s_add_i32 s30, s66, 0
	v_and_b32_e32 v9, 32, v9
	v_bfe_i32 v6, v6, 0, 16
	v_and_b32_e32 v8, 24, v8
	v_and_b32_e32 v10, 4, v10
	v_and_or_b32 v11, v7, s49, v11
	s_add_i32 m0, s30, 0x10000
	v_or3_b32 v8, v11, v10, v8
	v_add_lshl_u32 v9, v9, v6, 1
	global_load_lds_dwordx4 v128, s[12:13] sc1
	s_add_i32 m0, s30, 0x12000
	v_lshl_add_u32 v134, v8, 11, v9
	s_add_u32 s18, s12, 0x40000
	global_load_lds_dwordx4 v134, s[12:13] sc1
	s_addc_u32 s19, s13, 0
	s_add_i32 m0, s30, 0x14000
	s_add_i32 s31, s30, 0x2000
	global_load_lds_dwordx4 v128, s[18:19] sc1
	s_add_i32 m0, s30, 0x16000
	v_lshl_add_u32 v132, v7, 11, v9
	global_load_lds_dwordx4 v134, s[18:19] sc1
	s_mov_b32 m0, s30
	s_add_u32 s18, s10, 0x40000
	global_load_lds_dwordx4 v130, s[10:11] sc1
	s_mov_b32 m0, s31
	s_addc_u32 s19, s11, 0
	s_add_i32 s34, s30, 0x4000
	global_load_lds_dwordx4 v132, s[10:11] sc1
	s_mov_b32 m0, s34
	s_add_i32 s35, s30, 0x6000
	v_lshl_add_u64 v[8:9], s[12:13], 0, v[128:129]
	v_mov_b32_e32 v135, v129
	global_load_lds_dwordx4 v130, s[18:19] sc1
	s_mov_b32 m0, s35
	v_lshl_add_u64 v[10:11], s[12:13], 0, v[134:135]
	v_mov_b32_e32 v131, v129
	global_load_lds_dwordx4 v132, s[18:19] sc1
	v_lshl_add_u64 v[8:9], v[8:9], 0, s[6:7]
	s_add_i32 m0, s30, 0x18000
	v_lshl_add_u64 v[12:13], s[10:11], 0, v[130:131]
	v_mov_b32_e32 v133, v129
	global_load_lds_dwordx4 v[8:9], off sc1
	v_lshl_add_u64 v[8:9], v[10:11], 0, s[6:7]
	s_add_i32 m0, s30, 0x1a000
	s_add_i32 s36, s30, 0x8000
	v_lshl_add_u64 v[14:15], s[10:11], 0, v[132:133]
	global_load_lds_dwordx4 v[8:9], off sc1
	v_lshl_add_u64 v[8:9], v[12:13], 0, s[6:7]
	s_mov_b32 m0, s36
	s_add_i32 s37, s30, 0xa000
	global_load_lds_dwordx4 v[8:9], off sc1
	v_lshl_add_u64 v[8:9], v[14:15], 0, s[6:7]
	s_mov_b32 m0, s37
	s_add_u32 s18, s12, 0x40080
	global_load_lds_dwordx4 v[8:9], off sc1
	s_addc_u32 s19, s13, 0
	s_add_i32 m0, s30, 0x1c000
	s_and_b64 vcc, exec, s[0:1]
	global_load_lds_dwordx4 v128, s[18:19] sc1
	s_add_i32 m0, s30, 0x1e000
	s_nop 0
	global_load_lds_dwordx4 v134, s[18:19] sc1
	s_cbranch_vccnz .LBB0_1231
	s_barrier
.LBB0_1231:
	v_and_b32_e32 v142, 15, v2
	v_and_b32_e32 v143, 48, v2
	v_lshlrev_b32_e32 v2, 2, v2
	s_lshl_b32 s14, s14, 21
	v_lshl_or_b32 v7, v142, 6, v143
	v_and_b32_e32 v2, 32, v2
	s_and_b32 s14, s14, 0x3800000
	s_lshl_b32 s15, s15, 19
	v_bitop3_b32 v8, v7, s52, v2 bitop3:0xde
	v_bitop3_b32 v144, v7, s53, v2 bitop3:0xde
	s_add_i32 s14, s14, s15
	v_lshlrev_b32_e32 v2, 14, v0
	s_add_u32 s38, s76, s14
	v_and_b32_e32 v2, 0xffff8000, v2
	s_addc_u32 s39, s77, 0
	v_lshl_add_u32 v1, v1, 11, v2
	v_and_b32_e32 v0, 1, v0
	v_lshl_or_b32 v0, v0, 6, v1
	s_add_u32 s14, s3, s14
	v_lshl_add_u32 v0, v3, 1, v0
	v_mov_b32_e32 v1, v129
	s_addc_u32 s15, s28, 0
	v_lshl_add_u64 v[136:137], s[14:15], 0, v[0:1]
	v_lshlrev_b32_e32 v0, 14, v4
	v_and_b32_e32 v0, 0xffff8000, v0
	v_lshl_add_u32 v0, v5, 11, v0
	v_and_b32_e32 v1, 1, v4
	v_lshl_or_b32 v0, v1, 6, v0
	s_waitcnt vmcnt(8)
	s_barrier
	s_waitcnt vmcnt(6)
	v_lshl_add_u32 v0, v6, 1, v0
	v_mov_b32_e32 v1, v129
	v_lshl_add_u64 v[138:139], s[14:15], 0, v[0:1]
	s_add_u32 s40, s29, s16
	s_addc_u32 s41, s33, 0
	s_mov_b32 s42, -2
	s_mov_b64 s[14:15], 0
	v_add_u32_e32 v145, 0, v8
	s_barrier
	s_add_u32 s16, s38, s14
	s_addc_u32 s17, s39, s15
	s_add_u32 s16, s16, 0x13d00100
	s_addc_u32 s17, s17, 0
	s_add_u32 s43, s40, s14
	s_addc_u32 s44, s41, s15
	s_cmpk_eq_i32 s14, 0x700
	s_cselect_b32 s19, s11, s17
	s_cselect_b32 s18, s10, s16
	s_cselect_b32 s17, s13, s44
	s_cselect_b32 s16, s12, s43
	s_add_i32 s43, 0, 0x14000
	v_add_u32_e32 v158, s67, v144
	v_add_u32_e32 v174, s43, v144
	ds_read_b128 v[146:149], v158
	ds_read_b128 v[150:153], v158 offset:1024
	ds_read_b128 v[154:157], v158 offset:2048
	ds_read_b128 v[158:161], v158 offset:3072
	ds_read_b128 v[162:165], v174
	ds_read_b128 v[166:169], v174 offset:1024
	ds_read_b128 v[170:173], v174 offset:2048
	ds_read_b128 v[174:177], v174 offset:3072
	v_lshl_add_u64 v[210:211], v[136:137], 0, s[14:15]
	s_add_i32 m0, s30, 0xc000
	ds_read_b128 v[178:181], v145
	ds_read_b128 v[182:185], v145 offset:1024
	ds_read_b128 v[186:189], v145 offset:2048
	ds_read_b128 v[190:193], v145 offset:3072
	ds_read_b128 v[194:197], v145 offset:4096
	ds_read_b128 v[198:201], v145 offset:5120
	ds_read_b128 v[202:205], v145 offset:6144
	ds_read_b128 v[206:209], v145 offset:7168
	global_load_lds_dwordx4 v[210:211], off sc1
	v_lshl_add_u64 v[210:211], v[138:139], 0, s[14:15]
	s_add_i32 m0, s30, 0xe000
	s_nop 0
	global_load_lds_dwordx4 v[210:211], off sc1
	s_waitcnt vmcnt(8)
	s_waitcnt lgkmcnt(0)
	s_barrier
	s_waitcnt lgkmcnt(0)
	v_mfma_f32_16x16x32_f16 v[124:127], v[146:149], v[178:181], 0
	v_mfma_f32_16x16x32_f16 v[120:123], v[154:157], v[178:181], 0
	v_mfma_f32_16x16x32_f16 v[108:111], v[146:149], v[186:189], 0
	v_mfma_f32_16x16x32_f16 v[104:107], v[154:157], v[186:189], 0
	v_mfma_f32_16x16x32_f16 v[92:95], v[146:149], v[194:197], 0
	v_mfma_f32_16x16x32_f16 v[88:91], v[154:157], v[194:197], 0
	v_mfma_f32_16x16x32_f16 v[76:79], v[146:149], v[202:205], 0
	v_mfma_f32_16x16x32_f16 v[72:75], v[154:157], v[202:205], 0
	v_mfma_f32_16x16x32_f16 v[124:127], v[150:153], v[182:185], v[124:127]
	v_mfma_f32_16x16x32_f16 v[120:123], v[158:161], v[182:185], v[120:123]
	v_mfma_f32_16x16x32_f16 v[108:111], v[150:153], v[190:193], v[108:111]
	v_mfma_f32_16x16x32_f16 v[104:107], v[158:161], v[190:193], v[104:107]
	v_mfma_f32_16x16x32_f16 v[92:95], v[150:153], v[198:201], v[92:95]
	v_mfma_f32_16x16x32_f16 v[88:91], v[158:161], v[198:201], v[88:91]
	v_mfma_f32_16x16x32_f16 v[76:79], v[150:153], v[206:209], v[76:79]
	v_mfma_f32_16x16x32_f16 v[72:75], v[158:161], v[206:209], v[72:75]
	v_mfma_f32_16x16x32_f16 v[116:119], v[162:165], v[178:181], 0
	v_mfma_f32_16x16x32_f16 v[112:115], v[170:173], v[178:181], 0
	v_mfma_f32_16x16x32_f16 v[100:103], v[162:165], v[186:189], 0
	v_mfma_f32_16x16x32_f16 v[96:99], v[170:173], v[186:189], 0
	v_mfma_f32_16x16x32_f16 v[84:87], v[162:165], v[194:197], 0
	v_mfma_f32_16x16x32_f16 v[80:83], v[170:173], v[194:197], 0
	v_mfma_f32_16x16x32_f16 v[68:71], v[162:165], v[202:205], 0
	v_mfma_f32_16x16x32_f16 v[64:67], v[170:173], v[202:205], 0
	v_mfma_f32_16x16x32_f16 v[116:119], v[166:169], v[182:185], v[116:119]
	v_mfma_f32_16x16x32_f16 v[112:115], v[174:177], v[182:185], v[112:115]
	v_mfma_f32_16x16x32_f16 v[100:103], v[166:169], v[190:193], v[100:103]
	v_mfma_f32_16x16x32_f16 v[96:99], v[174:177], v[190:193], v[96:99]
	v_mfma_f32_16x16x32_f16 v[84:87], v[166:169], v[198:201], v[84:87]
	v_mfma_f32_16x16x32_f16 v[80:83], v[174:177], v[198:201], v[80:83]
	v_mfma_f32_16x16x32_f16 v[68:71], v[166:169], v[206:209], v[68:71]
	v_mfma_f32_16x16x32_f16 v[64:67], v[174:177], v[206:209], v[64:67]
	s_barrier
	s_add_i32 s44, s67, s66
	v_lshl_add_u64 v[210:211], s[16:17], 0, v[128:129]
	s_mov_b32 m0, s44
	ds_read_b128 v[178:181], v145 offset:16384
	ds_read_b128 v[182:185], v145 offset:17408
	ds_read_b128 v[186:189], v145 offset:18432
	ds_read_b128 v[190:193], v145 offset:19456
	ds_read_b128 v[194:197], v145 offset:20480
	ds_read_b128 v[198:201], v145 offset:21504
	ds_read_b128 v[202:205], v145 offset:22528
	ds_read_b128 v[206:209], v145 offset:23552
	global_load_lds_dwordx4 v[210:211], off sc1
	s_add_i32 m0, s44, 0x2000
	s_add_u32 s44, s16, 0x40000
	v_lshl_add_u64 v[212:213], s[16:17], 0, v[134:135]
	s_addc_u32 s45, s17, 0
	s_add_i32 s43, s43, s66
	global_load_lds_dwordx4 v[212:213], off sc1
	v_lshl_add_u64 v[214:215], s[44:45], 0, v[128:129]
	s_mov_b32 m0, s43
	v_lshl_add_u64 v[216:217], s[18:19], 0, v[132:133]
	global_load_lds_dwordx4 v[214:215], off sc1
	v_lshl_add_u64 v[214:215], s[44:45], 0, v[134:135]
	s_add_i32 m0, s43, 0x2000
	s_nop 0
	global_load_lds_dwordx4 v[214:215], off sc1
	v_lshl_add_u64 v[214:215], s[18:19], 0, v[130:131]
	s_mov_b32 m0, s30
	s_nop 0
	global_load_lds_dwordx4 v[214:215], off sc1
	s_mov_b32 m0, s31
	s_nop 0
	global_load_lds_dwordx4 v[216:217], off sc1
	s_waitcnt vmcnt(8)
	s_waitcnt lgkmcnt(0)
	s_barrier
	s_waitcnt lgkmcnt(0)
	v_mfma_f32_16x16x32_f16 v[60:63], v[146:149], v[178:181], 0
	v_mfma_f32_16x16x32_f16 v[56:59], v[154:157], v[178:181], 0
	v_mfma_f32_16x16x32_f16 v[44:47], v[146:149], v[186:189], 0
	v_mfma_f32_16x16x32_f16 v[40:43], v[154:157], v[186:189], 0
	v_mfma_f32_16x16x32_f16 v[28:31], v[146:149], v[194:197], 0
	v_mfma_f32_16x16x32_f16 v[24:27], v[154:157], v[194:197], 0
	v_mfma_f32_16x16x32_f16 v[12:15], v[146:149], v[202:205], 0
	v_mfma_f32_16x16x32_f16 v[8:11], v[154:157], v[202:205], 0
	v_mfma_f32_16x16x32_f16 v[60:63], v[150:153], v[182:185], v[60:63]
	v_mfma_f32_16x16x32_f16 v[56:59], v[158:161], v[182:185], v[56:59]
	v_mfma_f32_16x16x32_f16 v[44:47], v[150:153], v[190:193], v[44:47]
	v_mfma_f32_16x16x32_f16 v[40:43], v[158:161], v[190:193], v[40:43]
	v_mfma_f32_16x16x32_f16 v[28:31], v[150:153], v[198:201], v[28:31]
	v_mfma_f32_16x16x32_f16 v[24:27], v[158:161], v[198:201], v[24:27]
	v_mfma_f32_16x16x32_f16 v[12:15], v[150:153], v[206:209], v[12:15]
	v_mfma_f32_16x16x32_f16 v[8:11], v[158:161], v[206:209], v[8:11]
	v_mfma_f32_16x16x32_f16 v[52:55], v[162:165], v[178:181], 0
	v_mfma_f32_16x16x32_f16 v[48:51], v[170:173], v[178:181], 0
	v_mfma_f32_16x16x32_f16 v[36:39], v[162:165], v[186:189], 0
	v_mfma_f32_16x16x32_f16 v[32:35], v[170:173], v[186:189], 0
	v_mfma_f32_16x16x32_f16 v[20:23], v[162:165], v[194:197], 0
	v_mfma_f32_16x16x32_f16 v[16:19], v[170:173], v[194:197], 0
	v_mfma_f32_16x16x32_f16 v[4:7], v[162:165], v[202:205], 0
	v_mfma_f32_16x16x32_f16 v[0:3], v[170:173], v[202:205], 0
	v_mfma_f32_16x16x32_f16 v[52:55], v[166:169], v[182:185], v[52:55]
	v_mfma_f32_16x16x32_f16 v[48:51], v[174:177], v[182:185], v[48:51]
	v_mfma_f32_16x16x32_f16 v[36:39], v[166:169], v[190:193], v[36:39]
	v_mfma_f32_16x16x32_f16 v[32:35], v[174:177], v[190:193], v[32:35]
	v_mfma_f32_16x16x32_f16 v[20:23], v[166:169], v[198:201], v[20:23]
	v_mfma_f32_16x16x32_f16 v[16:19], v[174:177], v[198:201], v[16:19]
	v_mfma_f32_16x16x32_f16 v[4:7], v[166:169], v[206:209], v[4:7]
	v_mfma_f32_16x16x32_f16 v[0:3], v[174:177], v[206:209], v[0:3]
	s_barrier
	s_add_i32 s43, 0, 0x18000
	s_add_i32 s44, 0, 0x1c000
	v_add_u32_e32 v158, s43, v144
	v_add_u32_e32 v174, s44, v144
	ds_read_b128 v[146:149], v158
	ds_read_b128 v[150:153], v158 offset:1024
	ds_read_b128 v[154:157], v158 offset:2048
	ds_read_b128 v[158:161], v158 offset:3072
	ds_read_b128 v[162:165], v174
	ds_read_b128 v[166:169], v174 offset:1024
	ds_read_b128 v[170:173], v174 offset:2048
	ds_read_b128 v[174:177], v174 offset:3072
	s_add_u32 s18, s18, 0x40000
	s_addc_u32 s19, s19, 0
	s_mov_b32 m0, s34
	v_lshl_add_u64 v[218:219], s[18:19], 0, v[130:131]
	ds_read_b128 v[178:181], v145 offset:32768
	ds_read_b128 v[182:185], v145 offset:33792
	ds_read_b128 v[186:189], v145 offset:34816
	ds_read_b128 v[190:193], v145 offset:35840
	ds_read_b128 v[194:197], v145 offset:36864
	ds_read_b128 v[198:201], v145 offset:37888
	ds_read_b128 v[202:205], v145 offset:38912
	ds_read_b128 v[206:209], v145 offset:39936
	global_load_lds_dwordx4 v[218:219], off sc1
	v_lshl_add_u64 v[218:219], s[18:19], 0, v[132:133]
	s_mov_b32 m0, s35
	s_nop 0
	global_load_lds_dwordx4 v[218:219], off sc1
	s_waitcnt vmcnt(8)
	s_waitcnt lgkmcnt(0)
	s_barrier
	s_waitcnt lgkmcnt(0)
	v_mfma_f32_16x16x32_f16 v[124:127], v[146:149], v[178:181], v[124:127]
	v_mfma_f32_16x16x32_f16 v[120:123], v[154:157], v[178:181], v[120:123]
	v_mfma_f32_16x16x32_f16 v[108:111], v[146:149], v[186:189], v[108:111]
	v_mfma_f32_16x16x32_f16 v[104:107], v[154:157], v[186:189], v[104:107]
	v_mfma_f32_16x16x32_f16 v[92:95], v[146:149], v[194:197], v[92:95]
	v_mfma_f32_16x16x32_f16 v[88:91], v[154:157], v[194:197], v[88:91]
	v_mfma_f32_16x16x32_f16 v[76:79], v[146:149], v[202:205], v[76:79]
	v_mfma_f32_16x16x32_f16 v[72:75], v[154:157], v[202:205], v[72:75]
	v_mfma_f32_16x16x32_f16 v[124:127], v[150:153], v[182:185], v[124:127]
	v_mfma_f32_16x16x32_f16 v[120:123], v[158:161], v[182:185], v[120:123]
	v_mfma_f32_16x16x32_f16 v[108:111], v[150:153], v[190:193], v[108:111]
	v_mfma_f32_16x16x32_f16 v[104:107], v[158:161], v[190:193], v[104:107]
	v_mfma_f32_16x16x32_f16 v[92:95], v[150:153], v[198:201], v[92:95]
	v_mfma_f32_16x16x32_f16 v[88:91], v[158:161], v[198:201], v[88:91]
	v_mfma_f32_16x16x32_f16 v[76:79], v[150:153], v[206:209], v[76:79]
	v_mfma_f32_16x16x32_f16 v[72:75], v[158:161], v[206:209], v[72:75]
	v_mfma_f32_16x16x32_f16 v[116:119], v[162:165], v[178:181], v[116:119]
	v_mfma_f32_16x16x32_f16 v[112:115], v[170:173], v[178:181], v[112:115]
	v_mfma_f32_16x16x32_f16 v[100:103], v[162:165], v[186:189], v[100:103]
	v_mfma_f32_16x16x32_f16 v[96:99], v[170:173], v[186:189], v[96:99]
	v_mfma_f32_16x16x32_f16 v[84:87], v[162:165], v[194:197], v[84:87]
	v_mfma_f32_16x16x32_f16 v[80:83], v[170:173], v[194:197], v[80:83]
	v_mfma_f32_16x16x32_f16 v[68:71], v[162:165], v[202:205], v[68:71]
	v_mfma_f32_16x16x32_f16 v[64:67], v[170:173], v[202:205], v[64:67]
	v_mfma_f32_16x16x32_f16 v[116:119], v[166:169], v[182:185], v[116:119]
	v_mfma_f32_16x16x32_f16 v[112:115], v[174:177], v[182:185], v[112:115]
	v_mfma_f32_16x16x32_f16 v[100:103], v[166:169], v[190:193], v[100:103]
	v_mfma_f32_16x16x32_f16 v[96:99], v[174:177], v[190:193], v[96:99]
	v_mfma_f32_16x16x32_f16 v[84:87], v[166:169], v[198:201], v[84:87]
	v_mfma_f32_16x16x32_f16 v[80:83], v[174:177], v[198:201], v[80:83]
	v_mfma_f32_16x16x32_f16 v[68:71], v[166:169], v[206:209], v[68:71]
	v_mfma_f32_16x16x32_f16 v[64:67], v[174:177], v[206:209], v[64:67]
	s_barrier
	s_add_i32 s18, s43, s66
	v_lshl_add_u64 v[210:211], v[210:211], 0, s[6:7]
	s_mov_b32 m0, s18
	ds_read_b128 v[178:181], v145 offset:49152
	ds_read_b128 v[182:185], v145 offset:50176
	ds_read_b128 v[186:189], v145 offset:51200
	ds_read_b128 v[190:193], v145 offset:52224
	ds_read_b128 v[194:197], v145 offset:53248
	ds_read_b128 v[198:201], v145 offset:54272
	ds_read_b128 v[202:205], v145 offset:55296
	ds_read_b128 v[206:209], v145 offset:56320
	global_load_lds_dwordx4 v[210:211], off sc1
	s_add_i32 m0, s18, 0x2000
	s_add_u32 s16, s16, 0x40080
	v_lshl_add_u64 v[210:211], v[212:213], 0, s[6:7]
	s_addc_u32 s17, s17, 0
	s_add_i32 s18, s44, s66
	global_load_lds_dwordx4 v[210:211], off sc1
	v_lshl_add_u64 v[210:211], s[16:17], 0, v[128:129]
	s_mov_b32 m0, s18
	s_nop 0
	global_load_lds_dwordx4 v[210:211], off sc1
	v_lshl_add_u64 v[210:211], s[16:17], 0, v[134:135]
	s_add_i32 m0, s18, 0x2000
	s_nop 0
	global_load_lds_dwordx4 v[210:211], off sc1
	v_lshl_add_u64 v[210:211], v[214:215], 0, s[6:7]
	s_mov_b32 m0, s36
	s_nop 0
	global_load_lds_dwordx4 v[210:211], off sc1
	v_lshl_add_u64 v[210:211], v[216:217], 0, s[6:7]
	s_mov_b32 m0, s37
	s_nop 0
	global_load_lds_dwordx4 v[210:211], off sc1
	s_waitcnt vmcnt(8)
	s_waitcnt lgkmcnt(0)
	s_barrier
	s_waitcnt lgkmcnt(0)
	v_mfma_f32_16x16x32_f16 v[60:63], v[146:149], v[178:181], v[60:63]
	v_mfma_f32_16x16x32_f16 v[56:59], v[154:157], v[178:181], v[56:59]
	v_mfma_f32_16x16x32_f16 v[44:47], v[146:149], v[186:189], v[44:47]
	v_mfma_f32_16x16x32_f16 v[40:43], v[154:157], v[186:189], v[40:43]
	v_mfma_f32_16x16x32_f16 v[28:31], v[146:149], v[194:197], v[28:31]
	v_mfma_f32_16x16x32_f16 v[24:27], v[154:157], v[194:197], v[24:27]
	v_mfma_f32_16x16x32_f16 v[12:15], v[146:149], v[202:205], v[12:15]
	v_mfma_f32_16x16x32_f16 v[8:11], v[154:157], v[202:205], v[8:11]
	v_mfma_f32_16x16x32_f16 v[60:63], v[150:153], v[182:185], v[60:63]
	v_mfma_f32_16x16x32_f16 v[56:59], v[158:161], v[182:185], v[56:59]
	v_mfma_f32_16x16x32_f16 v[44:47], v[150:153], v[190:193], v[44:47]
	v_mfma_f32_16x16x32_f16 v[40:43], v[158:161], v[190:193], v[40:43]
	v_mfma_f32_16x16x32_f16 v[28:31], v[150:153], v[198:201], v[28:31]
	v_mfma_f32_16x16x32_f16 v[24:27], v[158:161], v[198:201], v[24:27]
	v_mfma_f32_16x16x32_f16 v[12:15], v[150:153], v[206:209], v[12:15]
	v_mfma_f32_16x16x32_f16 v[8:11], v[158:161], v[206:209], v[8:11]
	v_mfma_f32_16x16x32_f16 v[52:55], v[162:165], v[178:181], v[52:55]
	v_mfma_f32_16x16x32_f16 v[48:51], v[170:173], v[178:181], v[48:51]
	v_mfma_f32_16x16x32_f16 v[36:39], v[162:165], v[186:189], v[36:39]
	v_mfma_f32_16x16x32_f16 v[32:35], v[170:173], v[186:189], v[32:35]
	v_mfma_f32_16x16x32_f16 v[20:23], v[162:165], v[194:197], v[20:23]
	v_mfma_f32_16x16x32_f16 v[16:19], v[170:173], v[194:197], v[16:19]
	v_mfma_f32_16x16x32_f16 v[4:7], v[162:165], v[202:205], v[4:7]
	v_mfma_f32_16x16x32_f16 v[0:3], v[170:173], v[202:205], v[0:3]
	v_mfma_f32_16x16x32_f16 v[52:55], v[166:169], v[182:185], v[52:55]
	v_mfma_f32_16x16x32_f16 v[48:51], v[174:177], v[182:185], v[48:51]
	v_mfma_f32_16x16x32_f16 v[36:39], v[166:169], v[190:193], v[36:39]
	v_mfma_f32_16x16x32_f16 v[32:35], v[174:177], v[190:193], v[32:35]
	v_mfma_f32_16x16x32_f16 v[20:23], v[166:169], v[198:201], v[20:23]
	v_mfma_f32_16x16x32_f16 v[16:19], v[174:177], v[198:201], v[16:19]
	v_mfma_f32_16x16x32_f16 v[4:7], v[166:169], v[206:209], v[4:7]
	v_mfma_f32_16x16x32_f16 v[0:3], v[174:177], v[206:209], v[0:3]
	s_barrier
	s_add_i32 s42, s42, 2
	s_add_u32 s14, s14, 0x100
	s_addc_u32 s15, s15, 0
	s_cmp_gt_u32 s42, 13
.LBB0_1232:
	s_add_u32 s16, s38, s14
	s_addc_u32 s17, s39, s15
	s_add_u32 s16, s16, 0x13d00100
	s_addc_u32 s17, s17, 0
	s_add_u32 s43, s40, s14
	s_addc_u32 s44, s41, s15
	s_cmpk_eq_i32 s14, 0x700
	s_cselect_b32 s19, s11, s17
	s_cselect_b32 s18, s10, s16
	s_cselect_b32 s17, s13, s44
	s_cselect_b32 s16, s12, s43
	s_add_i32 s43, 0, 0x14000
	v_add_u32_e32 v158, s67, v144
	v_add_u32_e32 v174, s43, v144
	ds_read_b128 v[146:149], v158
	ds_read_b128 v[150:153], v158 offset:1024
	ds_read_b128 v[154:157], v158 offset:2048
	ds_read_b128 v[158:161], v158 offset:3072
	ds_read_b128 v[162:165], v174
	ds_read_b128 v[166:169], v174 offset:1024
	ds_read_b128 v[170:173], v174 offset:2048
	ds_read_b128 v[174:177], v174 offset:3072
	v_lshl_add_u64 v[210:211], v[136:137], 0, s[14:15]
	s_add_i32 m0, s30, 0xc000
	ds_read_b128 v[178:181], v145
	ds_read_b128 v[182:185], v145 offset:1024
	ds_read_b128 v[186:189], v145 offset:2048
	ds_read_b128 v[190:193], v145 offset:3072
	ds_read_b128 v[194:197], v145 offset:4096
	ds_read_b128 v[198:201], v145 offset:5120
	ds_read_b128 v[202:205], v145 offset:6144
	ds_read_b128 v[206:209], v145 offset:7168
	global_load_lds_dwordx4 v[210:211], off sc1
	v_lshl_add_u64 v[210:211], v[138:139], 0, s[14:15]
	s_add_i32 m0, s30, 0xe000
	s_nop 0
	global_load_lds_dwordx4 v[210:211], off sc1
	s_waitcnt vmcnt(8)
	s_waitcnt lgkmcnt(0)
	s_barrier
	s_waitcnt lgkmcnt(0)
	v_mfma_f32_16x16x32_f16 v[124:127], v[146:149], v[178:181], v[124:127]
	v_mfma_f32_16x16x32_f16 v[120:123], v[154:157], v[178:181], v[120:123]
	v_mfma_f32_16x16x32_f16 v[108:111], v[146:149], v[186:189], v[108:111]
	v_mfma_f32_16x16x32_f16 v[104:107], v[154:157], v[186:189], v[104:107]
	v_mfma_f32_16x16x32_f16 v[92:95], v[146:149], v[194:197], v[92:95]
	v_mfma_f32_16x16x32_f16 v[88:91], v[154:157], v[194:197], v[88:91]
	v_mfma_f32_16x16x32_f16 v[76:79], v[146:149], v[202:205], v[76:79]
	v_mfma_f32_16x16x32_f16 v[72:75], v[154:157], v[202:205], v[72:75]
	v_mfma_f32_16x16x32_f16 v[124:127], v[150:153], v[182:185], v[124:127]
	v_mfma_f32_16x16x32_f16 v[120:123], v[158:161], v[182:185], v[120:123]
	v_mfma_f32_16x16x32_f16 v[108:111], v[150:153], v[190:193], v[108:111]
	v_mfma_f32_16x16x32_f16 v[104:107], v[158:161], v[190:193], v[104:107]
	v_mfma_f32_16x16x32_f16 v[92:95], v[150:153], v[198:201], v[92:95]
	v_mfma_f32_16x16x32_f16 v[88:91], v[158:161], v[198:201], v[88:91]
	v_mfma_f32_16x16x32_f16 v[76:79], v[150:153], v[206:209], v[76:79]
	v_mfma_f32_16x16x32_f16 v[72:75], v[158:161], v[206:209], v[72:75]
	v_mfma_f32_16x16x32_f16 v[116:119], v[162:165], v[178:181], v[116:119]
	v_mfma_f32_16x16x32_f16 v[112:115], v[170:173], v[178:181], v[112:115]
	v_mfma_f32_16x16x32_f16 v[100:103], v[162:165], v[186:189], v[100:103]
	v_mfma_f32_16x16x32_f16 v[96:99], v[170:173], v[186:189], v[96:99]
	v_mfma_f32_16x16x32_f16 v[84:87], v[162:165], v[194:197], v[84:87]
	v_mfma_f32_16x16x32_f16 v[80:83], v[170:173], v[194:197], v[80:83]
	v_mfma_f32_16x16x32_f16 v[68:71], v[162:165], v[202:205], v[68:71]
	v_mfma_f32_16x16x32_f16 v[64:67], v[170:173], v[202:205], v[64:67]
	v_mfma_f32_16x16x32_f16 v[116:119], v[166:169], v[182:185], v[116:119]
	v_mfma_f32_16x16x32_f16 v[112:115], v[174:177], v[182:185], v[112:115]
	v_mfma_f32_16x16x32_f16 v[100:103], v[166:169], v[190:193], v[100:103]
	v_mfma_f32_16x16x32_f16 v[96:99], v[174:177], v[190:193], v[96:99]
	v_mfma_f32_16x16x32_f16 v[84:87], v[166:169], v[198:201], v[84:87]
	v_mfma_f32_16x16x32_f16 v[80:83], v[174:177], v[198:201], v[80:83]
	v_mfma_f32_16x16x32_f16 v[68:71], v[166:169], v[206:209], v[68:71]
	v_mfma_f32_16x16x32_f16 v[64:67], v[174:177], v[206:209], v[64:67]
	s_barrier
	s_add_i32 s44, s67, s66
	v_lshl_add_u64 v[210:211], s[16:17], 0, v[128:129]
	s_mov_b32 m0, s44
	ds_read_b128 v[178:181], v145 offset:16384
	ds_read_b128 v[182:185], v145 offset:17408
	ds_read_b128 v[186:189], v145 offset:18432
	ds_read_b128 v[190:193], v145 offset:19456
	ds_read_b128 v[194:197], v145 offset:20480
	ds_read_b128 v[198:201], v145 offset:21504
	ds_read_b128 v[202:205], v145 offset:22528
	ds_read_b128 v[206:209], v145 offset:23552
	global_load_lds_dwordx4 v[210:211], off sc1
	s_add_i32 m0, s44, 0x2000
	s_add_u32 s44, s16, 0x40000
	v_lshl_add_u64 v[212:213], s[16:17], 0, v[134:135]
	s_addc_u32 s45, s17, 0
	s_add_i32 s43, s43, s66
	global_load_lds_dwordx4 v[212:213], off sc1
	v_lshl_add_u64 v[214:215], s[44:45], 0, v[128:129]
	s_mov_b32 m0, s43
	v_lshl_add_u64 v[216:217], s[18:19], 0, v[132:133]
	global_load_lds_dwordx4 v[214:215], off sc1
	v_lshl_add_u64 v[214:215], s[44:45], 0, v[134:135]
	s_add_i32 m0, s43, 0x2000
	s_nop 0
	global_load_lds_dwordx4 v[214:215], off sc1
	v_lshl_add_u64 v[214:215], s[18:19], 0, v[130:131]
	s_mov_b32 m0, s30
	s_nop 0
	global_load_lds_dwordx4 v[214:215], off sc1
	s_mov_b32 m0, s31
	s_nop 0
	global_load_lds_dwordx4 v[216:217], off sc1
	s_waitcnt vmcnt(8)
	s_waitcnt lgkmcnt(0)
	s_barrier
	s_waitcnt lgkmcnt(0)
	v_mfma_f32_16x16x32_f16 v[60:63], v[146:149], v[178:181], v[60:63]
	v_mfma_f32_16x16x32_f16 v[56:59], v[154:157], v[178:181], v[56:59]
	v_mfma_f32_16x16x32_f16 v[44:47], v[146:149], v[186:189], v[44:47]
	v_mfma_f32_16x16x32_f16 v[40:43], v[154:157], v[186:189], v[40:43]
	v_mfma_f32_16x16x32_f16 v[28:31], v[146:149], v[194:197], v[28:31]
	v_mfma_f32_16x16x32_f16 v[24:27], v[154:157], v[194:197], v[24:27]
	v_mfma_f32_16x16x32_f16 v[12:15], v[146:149], v[202:205], v[12:15]
	v_mfma_f32_16x16x32_f16 v[8:11], v[154:157], v[202:205], v[8:11]
	v_mfma_f32_16x16x32_f16 v[60:63], v[150:153], v[182:185], v[60:63]
	v_mfma_f32_16x16x32_f16 v[56:59], v[158:161], v[182:185], v[56:59]
	v_mfma_f32_16x16x32_f16 v[44:47], v[150:153], v[190:193], v[44:47]
	v_mfma_f32_16x16x32_f16 v[40:43], v[158:161], v[190:193], v[40:43]
	v_mfma_f32_16x16x32_f16 v[28:31], v[150:153], v[198:201], v[28:31]
	v_mfma_f32_16x16x32_f16 v[24:27], v[158:161], v[198:201], v[24:27]
	v_mfma_f32_16x16x32_f16 v[12:15], v[150:153], v[206:209], v[12:15]
	v_mfma_f32_16x16x32_f16 v[8:11], v[158:161], v[206:209], v[8:11]
	v_mfma_f32_16x16x32_f16 v[52:55], v[162:165], v[178:181], v[52:55]
	v_mfma_f32_16x16x32_f16 v[48:51], v[170:173], v[178:181], v[48:51]
	v_mfma_f32_16x16x32_f16 v[36:39], v[162:165], v[186:189], v[36:39]
	v_mfma_f32_16x16x32_f16 v[32:35], v[170:173], v[186:189], v[32:35]
	v_mfma_f32_16x16x32_f16 v[20:23], v[162:165], v[194:197], v[20:23]
	v_mfma_f32_16x16x32_f16 v[16:19], v[170:173], v[194:197], v[16:19]
	v_mfma_f32_16x16x32_f16 v[4:7], v[162:165], v[202:205], v[4:7]
	v_mfma_f32_16x16x32_f16 v[0:3], v[170:173], v[202:205], v[0:3]
	v_mfma_f32_16x16x32_f16 v[52:55], v[166:169], v[182:185], v[52:55]
	v_mfma_f32_16x16x32_f16 v[48:51], v[174:177], v[182:185], v[48:51]
	v_mfma_f32_16x16x32_f16 v[36:39], v[166:169], v[190:193], v[36:39]
	v_mfma_f32_16x16x32_f16 v[32:35], v[174:177], v[190:193], v[32:35]
	v_mfma_f32_16x16x32_f16 v[20:23], v[166:169], v[198:201], v[20:23]
	v_mfma_f32_16x16x32_f16 v[16:19], v[174:177], v[198:201], v[16:19]
	v_mfma_f32_16x16x32_f16 v[4:7], v[166:169], v[206:209], v[4:7]
	v_mfma_f32_16x16x32_f16 v[0:3], v[174:177], v[206:209], v[0:3]
	s_barrier
	s_add_i32 s43, 0, 0x18000
	s_add_i32 s44, 0, 0x1c000
	v_add_u32_e32 v158, s43, v144
	v_add_u32_e32 v174, s44, v144
	ds_read_b128 v[146:149], v158
	ds_read_b128 v[150:153], v158 offset:1024
	ds_read_b128 v[154:157], v158 offset:2048
	ds_read_b128 v[158:161], v158 offset:3072
	ds_read_b128 v[162:165], v174
	ds_read_b128 v[166:169], v174 offset:1024
	ds_read_b128 v[170:173], v174 offset:2048
	ds_read_b128 v[174:177], v174 offset:3072
	s_add_u32 s18, s18, 0x40000
	s_addc_u32 s19, s19, 0
	s_mov_b32 m0, s34
	v_lshl_add_u64 v[218:219], s[18:19], 0, v[130:131]
	ds_read_b128 v[178:181], v145 offset:32768
	ds_read_b128 v[182:185], v145 offset:33792
	ds_read_b128 v[186:189], v145 offset:34816
	ds_read_b128 v[190:193], v145 offset:35840
	ds_read_b128 v[194:197], v145 offset:36864
	ds_read_b128 v[198:201], v145 offset:37888
	ds_read_b128 v[202:205], v145 offset:38912
	ds_read_b128 v[206:209], v145 offset:39936
	global_load_lds_dwordx4 v[218:219], off sc1
	v_lshl_add_u64 v[218:219], s[18:19], 0, v[132:133]
	s_mov_b32 m0, s35
	s_nop 0
	global_load_lds_dwordx4 v[218:219], off sc1
	s_waitcnt vmcnt(8)
	s_waitcnt lgkmcnt(0)
	s_barrier
	s_waitcnt lgkmcnt(0)
	v_mfma_f32_16x16x32_f16 v[124:127], v[146:149], v[178:181], v[124:127]
	v_mfma_f32_16x16x32_f16 v[120:123], v[154:157], v[178:181], v[120:123]
	v_mfma_f32_16x16x32_f16 v[108:111], v[146:149], v[186:189], v[108:111]
	v_mfma_f32_16x16x32_f16 v[104:107], v[154:157], v[186:189], v[104:107]
	v_mfma_f32_16x16x32_f16 v[92:95], v[146:149], v[194:197], v[92:95]
	v_mfma_f32_16x16x32_f16 v[88:91], v[154:157], v[194:197], v[88:91]
	v_mfma_f32_16x16x32_f16 v[76:79], v[146:149], v[202:205], v[76:79]
	v_mfma_f32_16x16x32_f16 v[72:75], v[154:157], v[202:205], v[72:75]
	v_mfma_f32_16x16x32_f16 v[124:127], v[150:153], v[182:185], v[124:127]
	v_mfma_f32_16x16x32_f16 v[120:123], v[158:161], v[182:185], v[120:123]
	v_mfma_f32_16x16x32_f16 v[108:111], v[150:153], v[190:193], v[108:111]
	v_mfma_f32_16x16x32_f16 v[104:107], v[158:161], v[190:193], v[104:107]
	v_mfma_f32_16x16x32_f16 v[92:95], v[150:153], v[198:201], v[92:95]
	v_mfma_f32_16x16x32_f16 v[88:91], v[158:161], v[198:201], v[88:91]
	v_mfma_f32_16x16x32_f16 v[76:79], v[150:153], v[206:209], v[76:79]
	v_mfma_f32_16x16x32_f16 v[72:75], v[158:161], v[206:209], v[72:75]
	v_mfma_f32_16x16x32_f16 v[116:119], v[162:165], v[178:181], v[116:119]
	v_mfma_f32_16x16x32_f16 v[112:115], v[170:173], v[178:181], v[112:115]
	v_mfma_f32_16x16x32_f16 v[100:103], v[162:165], v[186:189], v[100:103]
	v_mfma_f32_16x16x32_f16 v[96:99], v[170:173], v[186:189], v[96:99]
	v_mfma_f32_16x16x32_f16 v[84:87], v[162:165], v[194:197], v[84:87]
	v_mfma_f32_16x16x32_f16 v[80:83], v[170:173], v[194:197], v[80:83]
	v_mfma_f32_16x16x32_f16 v[68:71], v[162:165], v[202:205], v[68:71]
	v_mfma_f32_16x16x32_f16 v[64:67], v[170:173], v[202:205], v[64:67]
	v_mfma_f32_16x16x32_f16 v[116:119], v[166:169], v[182:185], v[116:119]
	v_mfma_f32_16x16x32_f16 v[112:115], v[174:177], v[182:185], v[112:115]
	v_mfma_f32_16x16x32_f16 v[100:103], v[166:169], v[190:193], v[100:103]
	v_mfma_f32_16x16x32_f16 v[96:99], v[174:177], v[190:193], v[96:99]
	v_mfma_f32_16x16x32_f16 v[84:87], v[166:169], v[198:201], v[84:87]
	v_mfma_f32_16x16x32_f16 v[80:83], v[174:177], v[198:201], v[80:83]
	v_mfma_f32_16x16x32_f16 v[68:71], v[166:169], v[206:209], v[68:71]
	v_mfma_f32_16x16x32_f16 v[64:67], v[174:177], v[206:209], v[64:67]
	s_barrier
	s_add_i32 s18, s43, s66
	v_lshl_add_u64 v[210:211], v[210:211], 0, s[6:7]
	s_mov_b32 m0, s18
	ds_read_b128 v[178:181], v145 offset:49152
	ds_read_b128 v[182:185], v145 offset:50176
	ds_read_b128 v[186:189], v145 offset:51200
	ds_read_b128 v[190:193], v145 offset:52224
	ds_read_b128 v[194:197], v145 offset:53248
	ds_read_b128 v[198:201], v145 offset:54272
	ds_read_b128 v[202:205], v145 offset:55296
	ds_read_b128 v[206:209], v145 offset:56320
	global_load_lds_dwordx4 v[210:211], off sc1
	s_add_i32 m0, s18, 0x2000
	s_add_u32 s16, s16, 0x40080
	v_lshl_add_u64 v[210:211], v[212:213], 0, s[6:7]
	s_addc_u32 s17, s17, 0
	s_add_i32 s18, s44, s66
	global_load_lds_dwordx4 v[210:211], off sc1
	v_lshl_add_u64 v[210:211], s[16:17], 0, v[128:129]
	s_mov_b32 m0, s18
	s_nop 0
	global_load_lds_dwordx4 v[210:211], off sc1
	v_lshl_add_u64 v[210:211], s[16:17], 0, v[134:135]
	s_add_i32 m0, s18, 0x2000
	s_nop 0
	global_load_lds_dwordx4 v[210:211], off sc1
	v_lshl_add_u64 v[210:211], v[214:215], 0, s[6:7]
	s_mov_b32 m0, s36
	s_nop 0
	global_load_lds_dwordx4 v[210:211], off sc1
	v_lshl_add_u64 v[210:211], v[216:217], 0, s[6:7]
	s_mov_b32 m0, s37
	s_nop 0
	global_load_lds_dwordx4 v[210:211], off sc1
	s_waitcnt vmcnt(8)
	s_waitcnt lgkmcnt(0)
	s_barrier
	s_waitcnt lgkmcnt(0)
	v_mfma_f32_16x16x32_f16 v[60:63], v[146:149], v[178:181], v[60:63]
	v_mfma_f32_16x16x32_f16 v[56:59], v[154:157], v[178:181], v[56:59]
	v_mfma_f32_16x16x32_f16 v[44:47], v[146:149], v[186:189], v[44:47]
	v_mfma_f32_16x16x32_f16 v[40:43], v[154:157], v[186:189], v[40:43]
	v_mfma_f32_16x16x32_f16 v[28:31], v[146:149], v[194:197], v[28:31]
	v_mfma_f32_16x16x32_f16 v[24:27], v[154:157], v[194:197], v[24:27]
	v_mfma_f32_16x16x32_f16 v[12:15], v[146:149], v[202:205], v[12:15]
	v_mfma_f32_16x16x32_f16 v[8:11], v[154:157], v[202:205], v[8:11]
	v_mfma_f32_16x16x32_f16 v[60:63], v[150:153], v[182:185], v[60:63]
	v_mfma_f32_16x16x32_f16 v[56:59], v[158:161], v[182:185], v[56:59]
	v_mfma_f32_16x16x32_f16 v[44:47], v[150:153], v[190:193], v[44:47]
	v_mfma_f32_16x16x32_f16 v[40:43], v[158:161], v[190:193], v[40:43]
	v_mfma_f32_16x16x32_f16 v[28:31], v[150:153], v[198:201], v[28:31]
	v_mfma_f32_16x16x32_f16 v[24:27], v[158:161], v[198:201], v[24:27]
	v_mfma_f32_16x16x32_f16 v[12:15], v[150:153], v[206:209], v[12:15]
	v_mfma_f32_16x16x32_f16 v[8:11], v[158:161], v[206:209], v[8:11]
	v_mfma_f32_16x16x32_f16 v[52:55], v[162:165], v[178:181], v[52:55]
	v_mfma_f32_16x16x32_f16 v[48:51], v[170:173], v[178:181], v[48:51]
	v_mfma_f32_16x16x32_f16 v[36:39], v[162:165], v[186:189], v[36:39]
	v_mfma_f32_16x16x32_f16 v[32:35], v[170:173], v[186:189], v[32:35]
	v_mfma_f32_16x16x32_f16 v[20:23], v[162:165], v[194:197], v[20:23]
	v_mfma_f32_16x16x32_f16 v[16:19], v[170:173], v[194:197], v[16:19]
	v_mfma_f32_16x16x32_f16 v[4:7], v[162:165], v[202:205], v[4:7]
	v_mfma_f32_16x16x32_f16 v[0:3], v[170:173], v[202:205], v[0:3]
	v_mfma_f32_16x16x32_f16 v[52:55], v[166:169], v[182:185], v[52:55]
	v_mfma_f32_16x16x32_f16 v[48:51], v[174:177], v[182:185], v[48:51]
	v_mfma_f32_16x16x32_f16 v[36:39], v[166:169], v[190:193], v[36:39]
	v_mfma_f32_16x16x32_f16 v[32:35], v[174:177], v[190:193], v[32:35]
	v_mfma_f32_16x16x32_f16 v[20:23], v[166:169], v[198:201], v[20:23]
	v_mfma_f32_16x16x32_f16 v[16:19], v[174:177], v[198:201], v[16:19]
	v_mfma_f32_16x16x32_f16 v[4:7], v[166:169], v[206:209], v[4:7]
	v_mfma_f32_16x16x32_f16 v[0:3], v[174:177], v[206:209], v[0:3]
	s_barrier
	s_add_i32 s42, s42, 2
	s_add_u32 s14, s14, 0x100
	s_addc_u32 s15, s15, 0
	s_cmp_gt_u32 s42, 13
	s_cbranch_scc0 .LBB0_1232
	s_and_b64 vcc, exec, s[26:27]
	s_cbranch_vccz .LBB0_1235
	s_barrier

.LBB0_1323:
	s_or_b64 exec, exec, s[26:27]
	s_waitcnt vmcnt(0)

.Lp4_enter:
	ds_read_b32 v0, v141
	s_waitcnt lgkmcnt(0)
	v_readfirstlane_b32 s0, v0
	s_cmp_eq_u32 s0, -1
	s_cbranch_scc1 .LBB0_1383
	v_mbcnt_lo_u32_b32 v1, -1, 0
	v_mbcnt_hi_u32_b32 v1, -1, v1
	s_lshr_b32 s18, s0, 2
	v_lshl_or_b32 v4, v1, 4, s53
	v_ashrrev_i32_e32 v0, 31, v4
	v_lshrrev_b32_e32 v0, 22, v0
	v_add_u32_e32 v0, v4, v0
	v_ashrrev_i32_e32 v0, 10, v0
	v_mul_i32_i24_e32 v2, 0x400, v0
	v_sub_u32_e32 v2, v4, v2
	v_lshrrev_b32_e32 v3, 4, v2
	v_bitop3_b32 v3, v3, v2, 32 bitop3:0x6c
	v_lshlrev_b32_e32 v2, 3, v0
	v_and_b32_e32 v5, -16, v2
	v_ashrrev_i32_e32 v2, 31, v3
	v_lshrrev_b32_e32 v2, 26, v2
	v_add_u32_e32 v6, v3, v2
	v_ashrrev_i32_e32 v2, 6, v6
	v_and_b32_e32 v6, 0xc0, v6
	v_sub_u32_e32 v3, v3, v6
	v_lshlrev_b32_e32 v7, 5, v0
	v_ashrrev_i16_sdwa v3, v140, sext(v3) dst_sel:DWORD dst_unused:UNUSED_PAD src0_sel:DWORD src1_sel:BYTE_0
	v_and_b32_e32 v7, 32, v7
	v_bfe_i32 v3, v3, 0, 16
	v_add_u32_e32 v5, v2, v5
	v_and_b32_e32 v9, 3, v2
	v_add_lshl_u32 v7, v7, v3, 1
	v_lshlrev_b32_e32 v6, 1, v5
	v_lshrrev_b32_e32 v8, 2, v5
	v_and_or_b32 v9, v5, s65, v9
	v_lshl_add_u32 v130, v5, 11, v7
	v_add_u32_e32 v5, 0x2000, v4
	v_ashrrev_i32_e32 v4, 31, v5
	v_lshrrev_b32_e32 v4, 22, v4
	v_and_b32_e32 v6, 24, v6
	v_and_b32_e32 v8, 4, v8
	v_add_u32_e32 v4, v5, v4
	v_or3_b32 v6, v9, v8, v6
	v_ashrrev_i32_e32 v4, 10, v4
	v_lshl_add_u32 v128, v6, 11, v7
	v_mul_i32_i24_e32 v6, 0x400, v4
	v_sub_u32_e32 v5, v5, v6
	v_lshrrev_b32_e32 v6, 4, v5
	v_bitop3_b32 v6, v6, v5, 32 bitop3:0x6c
	v_lshlrev_b32_e32 v5, 3, v4
	v_and_b32_e32 v7, -16, v5
	v_ashrrev_i32_e32 v5, 31, v6
	v_lshrrev_b32_e32 v5, 26, v5
	v_add_u32_e32 v8, v6, v5
	v_ashrrev_i32_e32 v5, 6, v8
	v_and_b32_e32 v8, 0xffc0, v8
	v_sub_u32_e32 v6, v6, v8
	s_and_b32 s34, s0, 3
	v_lshrrev_b16_e32 v8, 7, v6
	v_and_b32_e32 v8, 1, v8
	s_lshl_b64 s[26:27], s[18:19], 19
	s_lshl_b32 s28, s34, 19
	v_add_u32_e32 v7, v5, v7
	v_add_u16_e32 v6, v6, v8
	s_add_u32 s0, s50, s28
	v_lshlrev_b32_e32 v9, 5, v4
	v_ashrrev_i16_sdwa v6, v140, sext(v6) dst_sel:DWORD dst_unused:UNUSED_PAD src0_sel:DWORD src1_sel:BYTE_0
	v_lshlrev_b32_e32 v8, 1, v7
	v_lshrrev_b32_e32 v10, 2, v7
	v_and_b32_e32 v11, 3, v5
	s_addc_u32 s1, s51, 0
	s_add_i32 s35, s53, 0
	v_and_b32_e32 v9, 32, v9
	v_bfe_i32 v6, v6, 0, 16
	v_and_b32_e32 v8, 24, v8
	v_and_b32_e32 v10, 4, v10
	v_and_or_b32 v11, v7, s65, v11
	s_add_i32 m0, s35, 0x10000
	v_or3_b32 v8, v11, v10, v8
	v_add_lshl_u32 v9, v9, v6, 1
	global_load_lds_dwordx4 v128, s[0:1] sc1
	s_add_i32 m0, s35, 0x12000
	v_lshl_add_u32 v134, v8, 11, v9
	s_add_u32 s24, s0, 0x40000
	global_load_lds_dwordx4 v134, s[0:1] sc1
	s_addc_u32 s25, s1, 0
	s_add_i32 m0, s35, 0x14000
	v_lshl_add_u32 v132, v7, 11, v9
	global_load_lds_dwordx4 v128, s[24:25] sc1
	s_add_i32 m0, s35, 0x16000
	v_lshl_add_u64 v[8:9], s[0:1], 0, v[128:129]
	global_load_lds_dwordx4 v134, s[24:25] sc1
	s_add_u32 s24, s3, s26
	s_addc_u32 s25, s33, s27
	s_add_i32 s36, s35, 0x2000
	s_mov_b32 m0, s35
	s_add_u32 s30, s24, 0x40000
	global_load_lds_dwordx4 v130, s[24:25] sc1
	s_mov_b32 m0, s36
	s_addc_u32 s31, s25, 0
	s_add_i32 s37, s35, 0x4000
	global_load_lds_dwordx4 v132, s[24:25] sc1
	s_mov_b32 m0, s37
	s_add_i32 s38, s35, 0x6000
	v_mov_b32_e32 v135, v129
	global_load_lds_dwordx4 v130, s[30:31] sc1
	s_mov_b32 m0, s38
	v_lshl_add_u64 v[10:11], s[0:1], 0, v[134:135]
	v_mov_b32_e32 v131, v129
	global_load_lds_dwordx4 v132, s[30:31] sc1
	v_lshl_add_u64 v[8:9], v[8:9], 0, s[20:21]
	s_add_i32 m0, s35, 0x18000
	v_lshl_add_u64 v[12:13], s[24:25], 0, v[130:131]
	v_mov_b32_e32 v133, v129
	global_load_lds_dwordx4 v[8:9], off sc1
	v_lshl_add_u64 v[8:9], v[10:11], 0, s[20:21]
	s_add_i32 m0, s35, 0x1a000
	s_add_i32 s39, s35, 0x8000
	v_lshl_add_u64 v[14:15], s[24:25], 0, v[132:133]
	global_load_lds_dwordx4 v[8:9], off sc1
	v_lshl_add_u64 v[8:9], v[12:13], 0, s[20:21]
	s_mov_b32 m0, s39
	s_add_i32 s40, s35, 0xa000
	global_load_lds_dwordx4 v[8:9], off sc1
	v_lshl_add_u64 v[8:9], v[14:15], 0, s[20:21]
	s_mov_b32 m0, s40
	s_add_u32 s30, s0, 0x40080
	global_load_lds_dwordx4 v[8:9], off sc1
	s_addc_u32 s31, s1, 0
	s_add_i32 m0, s35, 0x1c000
	s_andn2_b64 vcc, exec, s[14:15]
	global_load_lds_dwordx4 v128, s[30:31] sc1
	s_add_i32 m0, s35, 0x1e000
	s_nop 0
	global_load_lds_dwordx4 v134, s[30:31] sc1
	s_cbranch_vccnz .LBB0_1328
	s_barrier
.LBB0_1328:
	v_bfe_u32 v144, v1, 4, 2
	v_and_b32_e32 v7, 15, v1
	v_lshlrev_b32_e32 v145, 4, v144
	v_lshlrev_b32_e32 v1, 2, v1
	v_or_b32_e32 v146, s54, v7
	v_lshl_or_b32 v7, v7, 6, v145
	v_and_b32_e32 v1, 32, v1
	v_bitop3_b32 v147, v7, s56, v1 bitop3:0xde
	v_lshlrev_b32_e32 v1, 14, v0
	s_add_u32 s41, s76, s26
	v_and_b32_e32 v1, 0xffff8000, v1
	s_addc_u32 s42, s77, s27
	v_lshl_add_u32 v1, v2, 11, v1
	v_and_b32_e32 v0, 1, v0
	v_lshl_or_b32 v0, v0, 6, v1
	s_add_u32 s26, s60, s26
	v_lshl_add_u32 v0, v3, 1, v0
	v_mov_b32_e32 v1, v129
	s_addc_u32 s27, s61, s27
	v_lshl_add_u64 v[136:137], s[26:27], 0, v[0:1]
	v_lshlrev_b32_e32 v0, 14, v4
	v_and_b32_e32 v0, 0xffff8000, v0
	v_lshl_add_u32 v0, v5, 11, v0
	v_and_b32_e32 v1, 1, v4
	v_lshlrev_b32_e32 v8, 6, v146
	v_lshlrev_b32_e32 v9, 2, v146
	v_lshl_or_b32 v0, v1, 6, v0
	v_and_or_b32 v8, v8, s66, v145
	v_and_b32_e32 v9, 32, v9
	s_waitcnt vmcnt(8)
	s_barrier
	s_waitcnt vmcnt(6)
	v_lshl_add_u32 v0, v6, 1, v0
	v_mov_b32_e32 v1, v129
	v_bitop3_b32 v7, v8, s55, v9 bitop3:0xde
	v_lshl_add_u64 v[138:139], s[26:27], 0, v[0:1]
	s_add_u32 s43, s62, s28
	s_addc_u32 s44, s63, 0
	s_mov_b32 s45, -2
	s_mov_b64 s[26:27], 0
	v_add_u32_e32 v148, 0, v7
	s_barrier
	s_add_u32 s28, s41, s26
	s_addc_u32 s29, s42, s27
	s_add_u32 s28, s28, 0x7a00100
	s_addc_u32 s29, s29, 0
	s_add_u32 s46, s43, s26
	s_addc_u32 s47, s44, s27
	s_add_i32 s48, 0, 0x10000
	s_cmpk_eq_i32 s26, 0x700
	s_cselect_b32 s31, s25, s29
	s_cselect_b32 s30, s24, s28
	v_add_u32_e32 v149, s48, v147
	s_cselect_b32 s29, s1, s47
	s_cselect_b32 s28, s0, s46
	s_add_i32 s49, 0, 0x14000
	ds_read_b128 v[150:153], v149
	ds_read_b128 v[154:157], v149 offset:1024
	ds_read_b128 v[158:161], v149 offset:2048
	ds_read_b128 v[162:165], v149 offset:3072
	v_add_u32_e32 v149, s49, v147
	ds_read_b128 v[166:169], v149
	ds_read_b128 v[170:173], v149 offset:1024
	ds_read_b128 v[174:177], v149 offset:2048
	ds_read_b128 v[178:181], v149 offset:3072
	v_lshl_add_u64 v[214:215], v[136:137], 0, s[26:27]
	s_add_i32 m0, s35, 0xc000
	ds_read_b128 v[182:185], v148
	ds_read_b128 v[186:189], v148 offset:1024
	ds_read_b128 v[190:193], v148 offset:2048
	ds_read_b128 v[194:197], v148 offset:3072
	ds_read_b128 v[198:201], v148 offset:4096
	ds_read_b128 v[202:205], v148 offset:5120
	ds_read_b128 v[206:209], v148 offset:6144
	ds_read_b128 v[210:213], v148 offset:7168
	global_load_lds_dwordx4 v[214:215], off sc1
	v_lshl_add_u64 v[214:215], v[138:139], 0, s[26:27]
	s_add_i32 m0, s35, 0xe000
	s_nop 0
	global_load_lds_dwordx4 v[214:215], off sc1
	s_waitcnt vmcnt(8)
	s_waitcnt lgkmcnt(0)
	s_barrier
	s_waitcnt lgkmcnt(0)
	v_mfma_f32_16x16x32_f16 v[124:127], v[150:153], v[182:185], 0
	v_mfma_f32_16x16x32_f16 v[120:123], v[158:161], v[182:185], 0
	v_mfma_f32_16x16x32_f16 v[108:111], v[150:153], v[190:193], 0
	v_mfma_f32_16x16x32_f16 v[104:107], v[158:161], v[190:193], 0
	v_mfma_f32_16x16x32_f16 v[92:95], v[150:153], v[198:201], 0
	v_mfma_f32_16x16x32_f16 v[88:91], v[158:161], v[198:201], 0
	v_mfma_f32_16x16x32_f16 v[76:79], v[150:153], v[206:209], 0
	v_mfma_f32_16x16x32_f16 v[72:75], v[158:161], v[206:209], 0
	v_mfma_f32_16x16x32_f16 v[124:127], v[154:157], v[186:189], v[124:127]
	v_mfma_f32_16x16x32_f16 v[120:123], v[162:165], v[186:189], v[120:123]
	v_mfma_f32_16x16x32_f16 v[108:111], v[154:157], v[194:197], v[108:111]
	v_mfma_f32_16x16x32_f16 v[104:107], v[162:165], v[194:197], v[104:107]
	v_mfma_f32_16x16x32_f16 v[92:95], v[154:157], v[202:205], v[92:95]
	v_mfma_f32_16x16x32_f16 v[88:91], v[162:165], v[202:205], v[88:91]
	v_mfma_f32_16x16x32_f16 v[76:79], v[154:157], v[210:213], v[76:79]
	v_mfma_f32_16x16x32_f16 v[72:75], v[162:165], v[210:213], v[72:75]
	v_mfma_f32_16x16x32_f16 v[116:119], v[166:169], v[182:185], 0
	v_mfma_f32_16x16x32_f16 v[112:115], v[174:177], v[182:185], 0
	v_mfma_f32_16x16x32_f16 v[100:103], v[166:169], v[190:193], 0
	v_mfma_f32_16x16x32_f16 v[96:99], v[174:177], v[190:193], 0
	v_mfma_f32_16x16x32_f16 v[84:87], v[166:169], v[198:201], 0
	v_mfma_f32_16x16x32_f16 v[80:83], v[174:177], v[198:201], 0
	v_mfma_f32_16x16x32_f16 v[68:71], v[166:169], v[206:209], 0
	v_mfma_f32_16x16x32_f16 v[64:67], v[174:177], v[206:209], 0
	v_mfma_f32_16x16x32_f16 v[116:119], v[170:173], v[186:189], v[116:119]
	v_mfma_f32_16x16x32_f16 v[112:115], v[178:181], v[186:189], v[112:115]
	v_mfma_f32_16x16x32_f16 v[100:103], v[170:173], v[194:197], v[100:103]
	v_mfma_f32_16x16x32_f16 v[96:99], v[178:181], v[194:197], v[96:99]
	v_mfma_f32_16x16x32_f16 v[84:87], v[170:173], v[202:205], v[84:87]
	v_mfma_f32_16x16x32_f16 v[80:83], v[178:181], v[202:205], v[80:83]
	v_mfma_f32_16x16x32_f16 v[68:71], v[170:173], v[210:213], v[68:71]
	v_mfma_f32_16x16x32_f16 v[64:67], v[178:181], v[210:213], v[64:67]
	s_barrier
	s_add_i32 s46, s48, s53
	v_lshl_add_u64 v[214:215], s[28:29], 0, v[128:129]
	s_mov_b32 m0, s46
	ds_read_b128 v[182:185], v148 offset:16384
	ds_read_b128 v[186:189], v148 offset:17408
	ds_read_b128 v[190:193], v148 offset:18432
	ds_read_b128 v[194:197], v148 offset:19456
	ds_read_b128 v[198:201], v148 offset:20480
	ds_read_b128 v[202:205], v148 offset:21504
	ds_read_b128 v[206:209], v148 offset:22528
	ds_read_b128 v[210:213], v148 offset:23552
	global_load_lds_dwordx4 v[214:215], off sc1
	s_add_i32 m0, s46, 0x2000
	s_add_u32 s46, s28, 0x40000
	v_lshl_add_u64 v[216:217], s[28:29], 0, v[134:135]
	s_addc_u32 s47, s29, 0
	s_add_i32 s48, s49, s53
	global_load_lds_dwordx4 v[216:217], off sc1
	v_lshl_add_u64 v[218:219], s[46:47], 0, v[128:129]
	s_mov_b32 m0, s48
	v_lshl_add_u64 v[220:221], s[30:31], 0, v[132:133]
	global_load_lds_dwordx4 v[218:219], off sc1
	v_lshl_add_u64 v[218:219], s[46:47], 0, v[134:135]
	s_add_i32 m0, s48, 0x2000
	s_nop 0
	global_load_lds_dwordx4 v[218:219], off sc1
	v_lshl_add_u64 v[218:219], s[30:31], 0, v[130:131]
	s_mov_b32 m0, s35
	s_nop 0
	global_load_lds_dwordx4 v[218:219], off sc1
	s_mov_b32 m0, s36
	s_nop 0
	global_load_lds_dwordx4 v[220:221], off sc1
	s_waitcnt vmcnt(8)
	s_waitcnt lgkmcnt(0)
	s_barrier
	s_waitcnt lgkmcnt(0)
	v_mfma_f32_16x16x32_f16 v[60:63], v[150:153], v[182:185], 0
	v_mfma_f32_16x16x32_f16 v[56:59], v[158:161], v[182:185], 0
	v_mfma_f32_16x16x32_f16 v[44:47], v[150:153], v[190:193], 0
	v_mfma_f32_16x16x32_f16 v[40:43], v[158:161], v[190:193], 0
	v_mfma_f32_16x16x32_f16 v[28:31], v[150:153], v[198:201], 0
	v_mfma_f32_16x16x32_f16 v[24:27], v[158:161], v[198:201], 0
	v_mfma_f32_16x16x32_f16 v[12:15], v[150:153], v[206:209], 0
	v_mfma_f32_16x16x32_f16 v[8:11], v[158:161], v[206:209], 0
	v_mfma_f32_16x16x32_f16 v[60:63], v[154:157], v[186:189], v[60:63]
	v_mfma_f32_16x16x32_f16 v[56:59], v[162:165], v[186:189], v[56:59]
	v_mfma_f32_16x16x32_f16 v[44:47], v[154:157], v[194:197], v[44:47]
	v_mfma_f32_16x16x32_f16 v[40:43], v[162:165], v[194:197], v[40:43]
	v_mfma_f32_16x16x32_f16 v[28:31], v[154:157], v[202:205], v[28:31]
	v_mfma_f32_16x16x32_f16 v[24:27], v[162:165], v[202:205], v[24:27]
	v_mfma_f32_16x16x32_f16 v[12:15], v[154:157], v[210:213], v[12:15]
	v_mfma_f32_16x16x32_f16 v[8:11], v[162:165], v[210:213], v[8:11]
	v_mfma_f32_16x16x32_f16 v[52:55], v[166:169], v[182:185], 0
	v_mfma_f32_16x16x32_f16 v[48:51], v[174:177], v[182:185], 0
	v_mfma_f32_16x16x32_f16 v[36:39], v[166:169], v[190:193], 0
	v_mfma_f32_16x16x32_f16 v[32:35], v[174:177], v[190:193], 0
	v_mfma_f32_16x16x32_f16 v[20:23], v[166:169], v[198:201], 0
	v_mfma_f32_16x16x32_f16 v[16:19], v[174:177], v[198:201], 0
	v_mfma_f32_16x16x32_f16 v[4:7], v[166:169], v[206:209], 0
	v_mfma_f32_16x16x32_f16 v[0:3], v[174:177], v[206:209], 0
	v_mfma_f32_16x16x32_f16 v[52:55], v[170:173], v[186:189], v[52:55]
	v_mfma_f32_16x16x32_f16 v[48:51], v[178:181], v[186:189], v[48:51]
	v_mfma_f32_16x16x32_f16 v[36:39], v[170:173], v[194:197], v[36:39]
	v_mfma_f32_16x16x32_f16 v[32:35], v[178:181], v[194:197], v[32:35]
	v_mfma_f32_16x16x32_f16 v[20:23], v[170:173], v[202:205], v[20:23]
	v_mfma_f32_16x16x32_f16 v[16:19], v[178:181], v[202:205], v[16:19]
	v_mfma_f32_16x16x32_f16 v[4:7], v[170:173], v[210:213], v[4:7]
	v_mfma_f32_16x16x32_f16 v[0:3], v[178:181], v[210:213], v[0:3]
	s_barrier
	s_add_i32 s46, 0, 0x18000
	v_add_u32_e32 v149, s46, v147
	s_add_i32 s47, 0, 0x1c000
	ds_read_b128 v[150:153], v149
	ds_read_b128 v[154:157], v149 offset:1024
	ds_read_b128 v[158:161], v149 offset:2048
	ds_read_b128 v[162:165], v149 offset:3072
	v_add_u32_e32 v149, s47, v147
	ds_read_b128 v[166:169], v149
	ds_read_b128 v[170:173], v149 offset:1024
	ds_read_b128 v[174:177], v149 offset:2048
	ds_read_b128 v[178:181], v149 offset:3072
	s_add_u32 s30, s30, 0x40000
	s_addc_u32 s31, s31, 0
	s_mov_b32 m0, s37
	v_lshl_add_u64 v[222:223], s[30:31], 0, v[130:131]
	ds_read_b128 v[182:185], v148 offset:32768
	ds_read_b128 v[186:189], v148 offset:33792
	ds_read_b128 v[190:193], v148 offset:34816
	ds_read_b128 v[194:197], v148 offset:35840
	ds_read_b128 v[198:201], v148 offset:36864
	ds_read_b128 v[202:205], v148 offset:37888
	ds_read_b128 v[206:209], v148 offset:38912
	ds_read_b128 v[210:213], v148 offset:39936
	global_load_lds_dwordx4 v[222:223], off sc1
	v_lshl_add_u64 v[222:223], s[30:31], 0, v[132:133]
	s_mov_b32 m0, s38
	s_nop 0
	global_load_lds_dwordx4 v[222:223], off sc1
	s_waitcnt vmcnt(8)
	s_waitcnt lgkmcnt(0)
	s_barrier
	s_waitcnt lgkmcnt(0)
	v_mfma_f32_16x16x32_f16 v[124:127], v[150:153], v[182:185], v[124:127]
	v_mfma_f32_16x16x32_f16 v[120:123], v[158:161], v[182:185], v[120:123]
	v_mfma_f32_16x16x32_f16 v[108:111], v[150:153], v[190:193], v[108:111]
	v_mfma_f32_16x16x32_f16 v[104:107], v[158:161], v[190:193], v[104:107]
	v_mfma_f32_16x16x32_f16 v[92:95], v[150:153], v[198:201], v[92:95]
	v_mfma_f32_16x16x32_f16 v[88:91], v[158:161], v[198:201], v[88:91]
	v_mfma_f32_16x16x32_f16 v[76:79], v[150:153], v[206:209], v[76:79]
	v_mfma_f32_16x16x32_f16 v[72:75], v[158:161], v[206:209], v[72:75]
	v_mfma_f32_16x16x32_f16 v[124:127], v[154:157], v[186:189], v[124:127]
	v_mfma_f32_16x16x32_f16 v[120:123], v[162:165], v[186:189], v[120:123]
	v_mfma_f32_16x16x32_f16 v[108:111], v[154:157], v[194:197], v[108:111]
	v_mfma_f32_16x16x32_f16 v[104:107], v[162:165], v[194:197], v[104:107]
	v_mfma_f32_16x16x32_f16 v[92:95], v[154:157], v[202:205], v[92:95]
	v_mfma_f32_16x16x32_f16 v[88:91], v[162:165], v[202:205], v[88:91]
	v_mfma_f32_16x16x32_f16 v[76:79], v[154:157], v[210:213], v[76:79]
	v_mfma_f32_16x16x32_f16 v[72:75], v[162:165], v[210:213], v[72:75]
	v_mfma_f32_16x16x32_f16 v[116:119], v[166:169], v[182:185], v[116:119]
	v_mfma_f32_16x16x32_f16 v[112:115], v[174:177], v[182:185], v[112:115]
	v_mfma_f32_16x16x32_f16 v[100:103], v[166:169], v[190:193], v[100:103]
	v_mfma_f32_16x16x32_f16 v[96:99], v[174:177], v[190:193], v[96:99]
	v_mfma_f32_16x16x32_f16 v[84:87], v[166:169], v[198:201], v[84:87]
	v_mfma_f32_16x16x32_f16 v[80:83], v[174:177], v[198:201], v[80:83]
	v_mfma_f32_16x16x32_f16 v[68:71], v[166:169], v[206:209], v[68:71]
	v_mfma_f32_16x16x32_f16 v[64:67], v[174:177], v[206:209], v[64:67]
	v_mfma_f32_16x16x32_f16 v[116:119], v[170:173], v[186:189], v[116:119]
	v_mfma_f32_16x16x32_f16 v[112:115], v[178:181], v[186:189], v[112:115]
	v_mfma_f32_16x16x32_f16 v[100:103], v[170:173], v[194:197], v[100:103]
	v_mfma_f32_16x16x32_f16 v[96:99], v[178:181], v[194:197], v[96:99]
	v_mfma_f32_16x16x32_f16 v[84:87], v[170:173], v[202:205], v[84:87]
	v_mfma_f32_16x16x32_f16 v[80:83], v[178:181], v[202:205], v[80:83]
	v_mfma_f32_16x16x32_f16 v[68:71], v[170:173], v[210:213], v[68:71]
	v_mfma_f32_16x16x32_f16 v[64:67], v[178:181], v[210:213], v[64:67]
	s_barrier
	s_add_i32 s30, s46, s53
	v_lshl_add_u64 v[214:215], v[214:215], 0, s[20:21]
	s_mov_b32 m0, s30
	ds_read_b128 v[182:185], v148 offset:49152
	ds_read_b128 v[186:189], v148 offset:50176
	ds_read_b128 v[190:193], v148 offset:51200
	ds_read_b128 v[194:197], v148 offset:52224
	ds_read_b128 v[198:201], v148 offset:53248
	ds_read_b128 v[202:205], v148 offset:54272
	ds_read_b128 v[206:209], v148 offset:55296
	ds_read_b128 v[210:213], v148 offset:56320
	global_load_lds_dwordx4 v[214:215], off sc1
	s_add_i32 m0, s30, 0x2000
	s_add_u32 s28, s28, 0x40080
	v_lshl_add_u64 v[214:215], v[216:217], 0, s[20:21]
	s_addc_u32 s29, s29, 0
	s_add_i32 s30, s47, s53
	global_load_lds_dwordx4 v[214:215], off sc1
	v_lshl_add_u64 v[214:215], s[28:29], 0, v[128:129]
	s_mov_b32 m0, s30
	s_nop 0
	global_load_lds_dwordx4 v[214:215], off sc1
	v_lshl_add_u64 v[214:215], s[28:29], 0, v[134:135]
	s_add_i32 m0, s30, 0x2000
	s_nop 0
	global_load_lds_dwordx4 v[214:215], off sc1
	v_lshl_add_u64 v[214:215], v[218:219], 0, s[20:21]
	s_mov_b32 m0, s39
	s_nop 0
	global_load_lds_dwordx4 v[214:215], off sc1
	v_lshl_add_u64 v[214:215], v[220:221], 0, s[20:21]
	s_mov_b32 m0, s40
	s_nop 0
	global_load_lds_dwordx4 v[214:215], off sc1
	s_waitcnt vmcnt(8)
	s_waitcnt lgkmcnt(0)
	s_barrier
	s_waitcnt lgkmcnt(0)
	v_mfma_f32_16x16x32_f16 v[60:63], v[150:153], v[182:185], v[60:63]
	v_mfma_f32_16x16x32_f16 v[56:59], v[158:161], v[182:185], v[56:59]
	v_mfma_f32_16x16x32_f16 v[44:47], v[150:153], v[190:193], v[44:47]
	v_mfma_f32_16x16x32_f16 v[40:43], v[158:161], v[190:193], v[40:43]
	v_mfma_f32_16x16x32_f16 v[28:31], v[150:153], v[198:201], v[28:31]
	v_mfma_f32_16x16x32_f16 v[24:27], v[158:161], v[198:201], v[24:27]
	v_mfma_f32_16x16x32_f16 v[12:15], v[150:153], v[206:209], v[12:15]
	v_mfma_f32_16x16x32_f16 v[8:11], v[158:161], v[206:209], v[8:11]
	v_mfma_f32_16x16x32_f16 v[60:63], v[154:157], v[186:189], v[60:63]
	v_mfma_f32_16x16x32_f16 v[56:59], v[162:165], v[186:189], v[56:59]
	v_mfma_f32_16x16x32_f16 v[44:47], v[154:157], v[194:197], v[44:47]
	v_mfma_f32_16x16x32_f16 v[40:43], v[162:165], v[194:197], v[40:43]
	v_mfma_f32_16x16x32_f16 v[28:31], v[154:157], v[202:205], v[28:31]
	v_mfma_f32_16x16x32_f16 v[24:27], v[162:165], v[202:205], v[24:27]
	v_mfma_f32_16x16x32_f16 v[12:15], v[154:157], v[210:213], v[12:15]
	v_mfma_f32_16x16x32_f16 v[8:11], v[162:165], v[210:213], v[8:11]
	v_mfma_f32_16x16x32_f16 v[52:55], v[166:169], v[182:185], v[52:55]
	v_mfma_f32_16x16x32_f16 v[48:51], v[174:177], v[182:185], v[48:51]
	v_mfma_f32_16x16x32_f16 v[36:39], v[166:169], v[190:193], v[36:39]
	v_mfma_f32_16x16x32_f16 v[32:35], v[174:177], v[190:193], v[32:35]
	v_mfma_f32_16x16x32_f16 v[20:23], v[166:169], v[198:201], v[20:23]
	v_mfma_f32_16x16x32_f16 v[16:19], v[174:177], v[198:201], v[16:19]
	v_mfma_f32_16x16x32_f16 v[4:7], v[166:169], v[206:209], v[4:7]
	v_mfma_f32_16x16x32_f16 v[0:3], v[174:177], v[206:209], v[0:3]
	v_mfma_f32_16x16x32_f16 v[52:55], v[170:173], v[186:189], v[52:55]
	v_mfma_f32_16x16x32_f16 v[48:51], v[178:181], v[186:189], v[48:51]
	v_mfma_f32_16x16x32_f16 v[36:39], v[170:173], v[194:197], v[36:39]
	v_mfma_f32_16x16x32_f16 v[32:35], v[178:181], v[194:197], v[32:35]
	v_mfma_f32_16x16x32_f16 v[20:23], v[170:173], v[202:205], v[20:23]
	v_mfma_f32_16x16x32_f16 v[16:19], v[178:181], v[202:205], v[16:19]
	v_mfma_f32_16x16x32_f16 v[4:7], v[170:173], v[210:213], v[4:7]
	v_mfma_f32_16x16x32_f16 v[0:3], v[178:181], v[210:213], v[0:3]
	s_barrier
	s_add_i32 s45, s45, 2
	s_add_u32 s26, s26, 0x100
	s_addc_u32 s27, s27, 0
	s_cmp_gt_u32 s45, 13
.LBB0_1329:
	s_add_u32 s28, s41, s26
	s_addc_u32 s29, s42, s27
	s_add_u32 s28, s28, 0x7a00100
	s_addc_u32 s29, s29, 0
	s_add_u32 s46, s43, s26
	s_addc_u32 s47, s44, s27
	s_add_i32 s48, 0, 0x10000
	s_cmpk_eq_i32 s26, 0x700
	s_cselect_b32 s31, s25, s29
	s_cselect_b32 s30, s24, s28
	v_add_u32_e32 v149, s48, v147
	s_cselect_b32 s29, s1, s47
	s_cselect_b32 s28, s0, s46
	s_add_i32 s49, 0, 0x14000
	ds_read_b128 v[150:153], v149
	ds_read_b128 v[154:157], v149 offset:1024
	ds_read_b128 v[158:161], v149 offset:2048
	ds_read_b128 v[162:165], v149 offset:3072
	v_add_u32_e32 v149, s49, v147
	ds_read_b128 v[166:169], v149
	ds_read_b128 v[170:173], v149 offset:1024
	ds_read_b128 v[174:177], v149 offset:2048
	ds_read_b128 v[178:181], v149 offset:3072
	v_lshl_add_u64 v[214:215], v[136:137], 0, s[26:27]
	s_add_i32 m0, s35, 0xc000
	ds_read_b128 v[182:185], v148
	ds_read_b128 v[186:189], v148 offset:1024
	ds_read_b128 v[190:193], v148 offset:2048
	ds_read_b128 v[194:197], v148 offset:3072
	ds_read_b128 v[198:201], v148 offset:4096
	ds_read_b128 v[202:205], v148 offset:5120
	ds_read_b128 v[206:209], v148 offset:6144
	ds_read_b128 v[210:213], v148 offset:7168
	global_load_lds_dwordx4 v[214:215], off sc1
	v_lshl_add_u64 v[214:215], v[138:139], 0, s[26:27]
	s_add_i32 m0, s35, 0xe000
	s_nop 0
	global_load_lds_dwordx4 v[214:215], off sc1
	s_waitcnt vmcnt(8)
	s_waitcnt lgkmcnt(0)
	s_barrier
	s_waitcnt lgkmcnt(0)
	v_mfma_f32_16x16x32_f16 v[124:127], v[150:153], v[182:185], v[124:127]
	v_mfma_f32_16x16x32_f16 v[120:123], v[158:161], v[182:185], v[120:123]
	v_mfma_f32_16x16x32_f16 v[108:111], v[150:153], v[190:193], v[108:111]
	v_mfma_f32_16x16x32_f16 v[104:107], v[158:161], v[190:193], v[104:107]
	v_mfma_f32_16x16x32_f16 v[92:95], v[150:153], v[198:201], v[92:95]
	v_mfma_f32_16x16x32_f16 v[88:91], v[158:161], v[198:201], v[88:91]
	v_mfma_f32_16x16x32_f16 v[76:79], v[150:153], v[206:209], v[76:79]
	v_mfma_f32_16x16x32_f16 v[72:75], v[158:161], v[206:209], v[72:75]
	v_mfma_f32_16x16x32_f16 v[124:127], v[154:157], v[186:189], v[124:127]
	v_mfma_f32_16x16x32_f16 v[120:123], v[162:165], v[186:189], v[120:123]
	v_mfma_f32_16x16x32_f16 v[108:111], v[154:157], v[194:197], v[108:111]
	v_mfma_f32_16x16x32_f16 v[104:107], v[162:165], v[194:197], v[104:107]
	v_mfma_f32_16x16x32_f16 v[92:95], v[154:157], v[202:205], v[92:95]
	v_mfma_f32_16x16x32_f16 v[88:91], v[162:165], v[202:205], v[88:91]
	v_mfma_f32_16x16x32_f16 v[76:79], v[154:157], v[210:213], v[76:79]
	v_mfma_f32_16x16x32_f16 v[72:75], v[162:165], v[210:213], v[72:75]
	v_mfma_f32_16x16x32_f16 v[116:119], v[166:169], v[182:185], v[116:119]
	v_mfma_f32_16x16x32_f16 v[112:115], v[174:177], v[182:185], v[112:115]
	v_mfma_f32_16x16x32_f16 v[100:103], v[166:169], v[190:193], v[100:103]
	v_mfma_f32_16x16x32_f16 v[96:99], v[174:177], v[190:193], v[96:99]
	v_mfma_f32_16x16x32_f16 v[84:87], v[166:169], v[198:201], v[84:87]
	v_mfma_f32_16x16x32_f16 v[80:83], v[174:177], v[198:201], v[80:83]
	v_mfma_f32_16x16x32_f16 v[68:71], v[166:169], v[206:209], v[68:71]
	v_mfma_f32_16x16x32_f16 v[64:67], v[174:177], v[206:209], v[64:67]
	v_mfma_f32_16x16x32_f16 v[116:119], v[170:173], v[186:189], v[116:119]
	v_mfma_f32_16x16x32_f16 v[112:115], v[178:181], v[186:189], v[112:115]
	v_mfma_f32_16x16x32_f16 v[100:103], v[170:173], v[194:197], v[100:103]
	v_mfma_f32_16x16x32_f16 v[96:99], v[178:181], v[194:197], v[96:99]
	v_mfma_f32_16x16x32_f16 v[84:87], v[170:173], v[202:205], v[84:87]
	v_mfma_f32_16x16x32_f16 v[80:83], v[178:181], v[202:205], v[80:83]
	v_mfma_f32_16x16x32_f16 v[68:71], v[170:173], v[210:213], v[68:71]
	v_mfma_f32_16x16x32_f16 v[64:67], v[178:181], v[210:213], v[64:67]
	s_barrier
	s_add_i32 s46, s48, s53
	v_lshl_add_u64 v[214:215], s[28:29], 0, v[128:129]
	s_mov_b32 m0, s46
	ds_read_b128 v[182:185], v148 offset:16384
	ds_read_b128 v[186:189], v148 offset:17408
	ds_read_b128 v[190:193], v148 offset:18432
	ds_read_b128 v[194:197], v148 offset:19456
	ds_read_b128 v[198:201], v148 offset:20480
	ds_read_b128 v[202:205], v148 offset:21504
	ds_read_b128 v[206:209], v148 offset:22528
	ds_read_b128 v[210:213], v148 offset:23552
	global_load_lds_dwordx4 v[214:215], off sc1
	s_add_i32 m0, s46, 0x2000
	s_add_u32 s46, s28, 0x40000
	v_lshl_add_u64 v[216:217], s[28:29], 0, v[134:135]
	s_addc_u32 s47, s29, 0
	s_add_i32 s48, s49, s53
	global_load_lds_dwordx4 v[216:217], off sc1
	v_lshl_add_u64 v[218:219], s[46:47], 0, v[128:129]
	s_mov_b32 m0, s48
	v_lshl_add_u64 v[220:221], s[30:31], 0, v[132:133]
	global_load_lds_dwordx4 v[218:219], off sc1
	v_lshl_add_u64 v[218:219], s[46:47], 0, v[134:135]
	s_add_i32 m0, s48, 0x2000
	s_nop 0
	global_load_lds_dwordx4 v[218:219], off sc1
	v_lshl_add_u64 v[218:219], s[30:31], 0, v[130:131]
	s_mov_b32 m0, s35
	s_nop 0
	global_load_lds_dwordx4 v[218:219], off sc1
	s_mov_b32 m0, s36
	s_nop 0
	global_load_lds_dwordx4 v[220:221], off sc1
	s_waitcnt vmcnt(8)
	s_waitcnt lgkmcnt(0)
	s_barrier
	s_waitcnt lgkmcnt(0)
	v_mfma_f32_16x16x32_f16 v[60:63], v[150:153], v[182:185], v[60:63]
	v_mfma_f32_16x16x32_f16 v[56:59], v[158:161], v[182:185], v[56:59]
	v_mfma_f32_16x16x32_f16 v[44:47], v[150:153], v[190:193], v[44:47]
	v_mfma_f32_16x16x32_f16 v[40:43], v[158:161], v[190:193], v[40:43]
	v_mfma_f32_16x16x32_f16 v[28:31], v[150:153], v[198:201], v[28:31]
	v_mfma_f32_16x16x32_f16 v[24:27], v[158:161], v[198:201], v[24:27]
	v_mfma_f32_16x16x32_f16 v[12:15], v[150:153], v[206:209], v[12:15]
	v_mfma_f32_16x16x32_f16 v[8:11], v[158:161], v[206:209], v[8:11]
	v_mfma_f32_16x16x32_f16 v[60:63], v[154:157], v[186:189], v[60:63]
	v_mfma_f32_16x16x32_f16 v[56:59], v[162:165], v[186:189], v[56:59]
	v_mfma_f32_16x16x32_f16 v[44:47], v[154:157], v[194:197], v[44:47]
	v_mfma_f32_16x16x32_f16 v[40:43], v[162:165], v[194:197], v[40:43]
	v_mfma_f32_16x16x32_f16 v[28:31], v[154:157], v[202:205], v[28:31]
	v_mfma_f32_16x16x32_f16 v[24:27], v[162:165], v[202:205], v[24:27]
	v_mfma_f32_16x16x32_f16 v[12:15], v[154:157], v[210:213], v[12:15]
	v_mfma_f32_16x16x32_f16 v[8:11], v[162:165], v[210:213], v[8:11]
	v_mfma_f32_16x16x32_f16 v[52:55], v[166:169], v[182:185], v[52:55]
	v_mfma_f32_16x16x32_f16 v[48:51], v[174:177], v[182:185], v[48:51]
	v_mfma_f32_16x16x32_f16 v[36:39], v[166:169], v[190:193], v[36:39]
	v_mfma_f32_16x16x32_f16 v[32:35], v[174:177], v[190:193], v[32:35]
	v_mfma_f32_16x16x32_f16 v[20:23], v[166:169], v[198:201], v[20:23]
	v_mfma_f32_16x16x32_f16 v[16:19], v[174:177], v[198:201], v[16:19]
	v_mfma_f32_16x16x32_f16 v[4:7], v[166:169], v[206:209], v[4:7]
	v_mfma_f32_16x16x32_f16 v[0:3], v[174:177], v[206:209], v[0:3]
	v_mfma_f32_16x16x32_f16 v[52:55], v[170:173], v[186:189], v[52:55]
	v_mfma_f32_16x16x32_f16 v[48:51], v[178:181], v[186:189], v[48:51]
	v_mfma_f32_16x16x32_f16 v[36:39], v[170:173], v[194:197], v[36:39]
	v_mfma_f32_16x16x32_f16 v[32:35], v[178:181], v[194:197], v[32:35]
	v_mfma_f32_16x16x32_f16 v[20:23], v[170:173], v[202:205], v[20:23]
	v_mfma_f32_16x16x32_f16 v[16:19], v[178:181], v[202:205], v[16:19]
	v_mfma_f32_16x16x32_f16 v[4:7], v[170:173], v[210:213], v[4:7]
	v_mfma_f32_16x16x32_f16 v[0:3], v[178:181], v[210:213], v[0:3]
	s_barrier
	s_add_i32 s46, 0, 0x18000
	v_add_u32_e32 v149, s46, v147
	s_add_i32 s47, 0, 0x1c000
	ds_read_b128 v[150:153], v149
	ds_read_b128 v[154:157], v149 offset:1024
	ds_read_b128 v[158:161], v149 offset:2048
	ds_read_b128 v[162:165], v149 offset:3072
	v_add_u32_e32 v149, s47, v147
	ds_read_b128 v[166:169], v149
	ds_read_b128 v[170:173], v149 offset:1024
	ds_read_b128 v[174:177], v149 offset:2048
	ds_read_b128 v[178:181], v149 offset:3072
	s_add_u32 s30, s30, 0x40000
	s_addc_u32 s31, s31, 0
	s_mov_b32 m0, s37
	v_lshl_add_u64 v[222:223], s[30:31], 0, v[130:131]
	ds_read_b128 v[182:185], v148 offset:32768
	ds_read_b128 v[186:189], v148 offset:33792
	ds_read_b128 v[190:193], v148 offset:34816
	ds_read_b128 v[194:197], v148 offset:35840
	ds_read_b128 v[198:201], v148 offset:36864
	ds_read_b128 v[202:205], v148 offset:37888
	ds_read_b128 v[206:209], v148 offset:38912
	ds_read_b128 v[210:213], v148 offset:39936
	global_load_lds_dwordx4 v[222:223], off sc1
	v_lshl_add_u64 v[222:223], s[30:31], 0, v[132:133]
	s_mov_b32 m0, s38
	s_nop 0
	global_load_lds_dwordx4 v[222:223], off sc1
	s_waitcnt vmcnt(8)
	s_waitcnt lgkmcnt(0)
	s_barrier
	s_waitcnt lgkmcnt(0)
	v_mfma_f32_16x16x32_f16 v[124:127], v[150:153], v[182:185], v[124:127]
	v_mfma_f32_16x16x32_f16 v[120:123], v[158:161], v[182:185], v[120:123]
	v_mfma_f32_16x16x32_f16 v[108:111], v[150:153], v[190:193], v[108:111]
	v_mfma_f32_16x16x32_f16 v[104:107], v[158:161], v[190:193], v[104:107]
	v_mfma_f32_16x16x32_f16 v[92:95], v[150:153], v[198:201], v[92:95]
	v_mfma_f32_16x16x32_f16 v[88:91], v[158:161], v[198:201], v[88:91]
	v_mfma_f32_16x16x32_f16 v[76:79], v[150:153], v[206:209], v[76:79]
	v_mfma_f32_16x16x32_f16 v[72:75], v[158:161], v[206:209], v[72:75]
	v_mfma_f32_16x16x32_f16 v[124:127], v[154:157], v[186:189], v[124:127]
	v_mfma_f32_16x16x32_f16 v[120:123], v[162:165], v[186:189], v[120:123]
	v_mfma_f32_16x16x32_f16 v[108:111], v[154:157], v[194:197], v[108:111]
	v_mfma_f32_16x16x32_f16 v[104:107], v[162:165], v[194:197], v[104:107]
	v_mfma_f32_16x16x32_f16 v[92:95], v[154:157], v[202:205], v[92:95]
	v_mfma_f32_16x16x32_f16 v[88:91], v[162:165], v[202:205], v[88:91]
	v_mfma_f32_16x16x32_f16 v[76:79], v[154:157], v[210:213], v[76:79]
	v_mfma_f32_16x16x32_f16 v[72:75], v[162:165], v[210:213], v[72:75]
	v_mfma_f32_16x16x32_f16 v[116:119], v[166:169], v[182:185], v[116:119]
	v_mfma_f32_16x16x32_f16 v[112:115], v[174:177], v[182:185], v[112:115]
	v_mfma_f32_16x16x32_f16 v[100:103], v[166:169], v[190:193], v[100:103]
	v_mfma_f32_16x16x32_f16 v[96:99], v[174:177], v[190:193], v[96:99]
	v_mfma_f32_16x16x32_f16 v[84:87], v[166:169], v[198:201], v[84:87]
	v_mfma_f32_16x16x32_f16 v[80:83], v[174:177], v[198:201], v[80:83]
	v_mfma_f32_16x16x32_f16 v[68:71], v[166:169], v[206:209], v[68:71]
	v_mfma_f32_16x16x32_f16 v[64:67], v[174:177], v[206:209], v[64:67]
	v_mfma_f32_16x16x32_f16 v[116:119], v[170:173], v[186:189], v[116:119]
	v_mfma_f32_16x16x32_f16 v[112:115], v[178:181], v[186:189], v[112:115]
	v_mfma_f32_16x16x32_f16 v[100:103], v[170:173], v[194:197], v[100:103]
	v_mfma_f32_16x16x32_f16 v[96:99], v[178:181], v[194:197], v[96:99]
	v_mfma_f32_16x16x32_f16 v[84:87], v[170:173], v[202:205], v[84:87]
	v_mfma_f32_16x16x32_f16 v[80:83], v[178:181], v[202:205], v[80:83]
	v_mfma_f32_16x16x32_f16 v[68:71], v[170:173], v[210:213], v[68:71]
	v_mfma_f32_16x16x32_f16 v[64:67], v[178:181], v[210:213], v[64:67]
	s_barrier
	s_add_i32 s30, s46, s53
	v_lshl_add_u64 v[214:215], v[214:215], 0, s[20:21]
	s_mov_b32 m0, s30
	ds_read_b128 v[182:185], v148 offset:49152
	ds_read_b128 v[186:189], v148 offset:50176
	ds_read_b128 v[190:193], v148 offset:51200
	ds_read_b128 v[194:197], v148 offset:52224
	ds_read_b128 v[198:201], v148 offset:53248
	ds_read_b128 v[202:205], v148 offset:54272
	ds_read_b128 v[206:209], v148 offset:55296
	ds_read_b128 v[210:213], v148 offset:56320
	global_load_lds_dwordx4 v[214:215], off sc1
	s_add_i32 m0, s30, 0x2000
	s_add_u32 s28, s28, 0x40080
	v_lshl_add_u64 v[214:215], v[216:217], 0, s[20:21]
	s_addc_u32 s29, s29, 0
	s_add_i32 s30, s47, s53
	global_load_lds_dwordx4 v[214:215], off sc1
	v_lshl_add_u64 v[214:215], s[28:29], 0, v[128:129]
	s_mov_b32 m0, s30
	s_nop 0
	global_load_lds_dwordx4 v[214:215], off sc1
	v_lshl_add_u64 v[214:215], s[28:29], 0, v[134:135]
	s_add_i32 m0, s30, 0x2000
	s_nop 0
	global_load_lds_dwordx4 v[214:215], off sc1
	v_lshl_add_u64 v[214:215], v[218:219], 0, s[20:21]
	s_mov_b32 m0, s39
	s_nop 0
	global_load_lds_dwordx4 v[214:215], off sc1
	v_lshl_add_u64 v[214:215], v[220:221], 0, s[20:21]
	s_mov_b32 m0, s40
	s_nop 0
	global_load_lds_dwordx4 v[214:215], off sc1
	s_waitcnt vmcnt(8)
	s_waitcnt lgkmcnt(0)
	s_barrier
	s_waitcnt lgkmcnt(0)
	v_mfma_f32_16x16x32_f16 v[60:63], v[150:153], v[182:185], v[60:63]
	v_mfma_f32_16x16x32_f16 v[56:59], v[158:161], v[182:185], v[56:59]
	v_mfma_f32_16x16x32_f16 v[44:47], v[150:153], v[190:193], v[44:47]
	v_mfma_f32_16x16x32_f16 v[40:43], v[158:161], v[190:193], v[40:43]
	v_mfma_f32_16x16x32_f16 v[28:31], v[150:153], v[198:201], v[28:31]
	v_mfma_f32_16x16x32_f16 v[24:27], v[158:161], v[198:201], v[24:27]
	v_mfma_f32_16x16x32_f16 v[12:15], v[150:153], v[206:209], v[12:15]
	v_mfma_f32_16x16x32_f16 v[8:11], v[158:161], v[206:209], v[8:11]
	v_mfma_f32_16x16x32_f16 v[60:63], v[154:157], v[186:189], v[60:63]
	v_mfma_f32_16x16x32_f16 v[56:59], v[162:165], v[186:189], v[56:59]
	v_mfma_f32_16x16x32_f16 v[44:47], v[154:157], v[194:197], v[44:47]
	v_mfma_f32_16x16x32_f16 v[40:43], v[162:165], v[194:197], v[40:43]
	v_mfma_f32_16x16x32_f16 v[28:31], v[154:157], v[202:205], v[28:31]
	v_mfma_f32_16x16x32_f16 v[24:27], v[162:165], v[202:205], v[24:27]
	v_mfma_f32_16x16x32_f16 v[12:15], v[154:157], v[210:213], v[12:15]
	v_mfma_f32_16x16x32_f16 v[8:11], v[162:165], v[210:213], v[8:11]
	v_mfma_f32_16x16x32_f16 v[52:55], v[166:169], v[182:185], v[52:55]
	v_mfma_f32_16x16x32_f16 v[48:51], v[174:177], v[182:185], v[48:51]
	v_mfma_f32_16x16x32_f16 v[36:39], v[166:169], v[190:193], v[36:39]
	v_mfma_f32_16x16x32_f16 v[32:35], v[174:177], v[190:193], v[32:35]
	v_mfma_f32_16x16x32_f16 v[20:23], v[166:169], v[198:201], v[20:23]
	v_mfma_f32_16x16x32_f16 v[16:19], v[174:177], v[198:201], v[16:19]
	v_mfma_f32_16x16x32_f16 v[4:7], v[166:169], v[206:209], v[4:7]
	v_mfma_f32_16x16x32_f16 v[0:3], v[174:177], v[206:209], v[0:3]
	v_mfma_f32_16x16x32_f16 v[52:55], v[170:173], v[186:189], v[52:55]
	v_mfma_f32_16x16x32_f16 v[48:51], v[178:181], v[186:189], v[48:51]
	v_mfma_f32_16x16x32_f16 v[36:39], v[170:173], v[194:197], v[36:39]
	v_mfma_f32_16x16x32_f16 v[32:35], v[178:181], v[194:197], v[32:35]
	v_mfma_f32_16x16x32_f16 v[20:23], v[170:173], v[202:205], v[20:23]
	v_mfma_f32_16x16x32_f16 v[16:19], v[178:181], v[202:205], v[16:19]
	v_mfma_f32_16x16x32_f16 v[4:7], v[170:173], v[210:213], v[4:7]
	v_mfma_f32_16x16x32_f16 v[0:3], v[178:181], v[210:213], v[0:3]
	s_barrier
	s_add_i32 s45, s45, 2
	s_add_u32 s26, s26, 0x100
	s_addc_u32 s27, s27, 0
	s_cmp_gt_u32 s45, 13
	s_cbranch_scc0 .LBB0_1329
	s_and_b64 vcc, exec, s[16:17]
	s_cbranch_vccz .LBB0_1332
	s_barrier
